# fragment loads of all five split-K small-tile GEMMs issued early into dead registers with re-derived counted waits (K=2816 tile had ~30 dependent round trips)
# baseline (speedup 1.0000x reference)
; template <int K, class Epi> __device__ __forceinline__ void gemm_small2_rc(const bf16_t* A, const bf16_t* Bt, int row0, int col0, int wave, int lane, const Epi& E, unsigned char* lds) {
;     constexpr int KW = K / 8, NS = KW / 32;
;     const int i = lane & 15, q = lane >> 4;
;     const bf16_t* ap = A + (size_t)(row0 + i) * K + wave * KW + 8 * q; const bf16_t* bp = Bt + (size_t)(col0 + i) * K + wave * KW + 8 * q;
;     f32x4 acc[4][4];
; #pragma unroll
;     for (int cb = 0; cb < 4; ++cb)
; #pragma unroll
;         for (int rb = 0; rb < 4; ++rb) acc[cb][rb] = (f32x4){0.f, 0.f, 0.f, 0.f};
; #pragma unroll
;     for (int s0 = 0; s0 < NS; s0 += 4) {
;         bf16x8 a[4][4], b[4][4];
; #pragma unroll
;         for (int s = 0; s < 4; ++s) if (s0 + s < NS) {
; #pragma unroll
;             for (int x = 0; x < 4; ++x) { a[s][x] = *(const bf16x8*)(ap + (size_t)(16 * x) * K + 32 * (s0 + s)); b[s][x] = *(const bf16x8*)(bp + (size_t)(16 * x) * K + 32 * (s0 + s)); } }
; #pragma unroll
;         for (int s = 0; s < 4; ++s) if (s0 + s < NS) {
; #pragma unroll
;             for (int cb = 0; cb < 4; ++cb)
; #pragma unroll
;                 for (int rb = 0; rb < 4; ++rb) acc[cb][rb] = __builtin_amdgcn_mfma_f32_16x16x32_bf16(b[s][cb], a[s][rb], acc[cb][rb], 0, 0, 0); }
;     }
.LBB0_649:
	s_and_b32 s16, s1, 0xffffffc0
	v_mbcnt_lo_u32_b32 v15, -1, 0
	v_mbcnt_hi_u32_b32 v15, -1, v15
	s_and_b32 s6, s3, 0x7c0
	v_and_b32_e32 v122, 15, v15
	v_ashrrev_i32_e32 v123, 4, v15
	v_or_b32_e32 v4, s16, v122
	v_ashrrev_i32_e32 v5, 31, v4
	v_lshlrev_b32_e32 v0, 3, v123
	s_waitcnt lgkmcnt(0)
	v_ashrrev_i32_e32 v1, 31, v0
	v_lshlrev_b64 v[4:5], 11, v[4:5]
	v_lshlrev_b64 v[6:7], 1, v[0:1]
	v_lshl_add_u64 v[4:5], s[10:11], 0, v[4:5]
	v_lshl_add_u64 v[106:107], v[4:5], 0, v[6:7]
	v_add_co_u32_e32 v108, vcc, s19, v106
	v_or_b32_e32 v2, s6, v122
	s_nop 0
	v_addc_co_u32_e32 v109, vcc, 0, v107, vcc
	v_add_co_u32_e32 v110, vcc, s20, v106
	v_lshlrev_b32_e32 v8, 11, v2
	s_nop 0
	v_addc_co_u32_e32 v111, vcc, 0, v107, vcc
	v_lshl_add_u64 v[2:3], s[8:9], 0, v[8:9]
	v_add_co_u32_e32 v112, vcc, s21, v106
	v_lshl_add_u64 v[104:105], v[2:3], 0, v[6:7]
	global_load_dwordx4 v[128:131], v[104:105], off
	global_load_dwordx4 v[132:135], v[106:107], off
	global_load_dwordx4 v[136:139], v[108:109], off
	global_load_dwordx4 v[140:143], v[104:105], off offset:64
	global_load_dwordx4 v[144:147], v[106:107], off offset:64
	global_load_dwordx4 v[148:151], v[110:111], off
	global_load_dwordx4 v[152:155], v[108:109], off offset:64
	s_nop 0
	v_addc_co_u32_e32 v113, vcc, 0, v107, vcc
	global_load_dwordx4 v[156:159], v[112:113], off
	global_load_dwordx4 v[160:163], v[110:111], off offset:64
	global_load_dwordx4 v[164:167], v[112:113], off offset:64
	v_add_co_u32_e32 v114, vcc, s19, v104
	s_nop 1
	v_addc_co_u32_e32 v115, vcc, 0, v105, vcc
	global_load_dwordx4 v[168:171], v[114:115], off
	global_load_dwordx4 v[172:175], v[114:115], off offset:64
	v_add_co_u32_e32 v116, vcc, s20, v104
	s_nop 1
	v_addc_co_u32_e32 v117, vcc, 0, v105, vcc
	global_load_dwordx4 v[176:179], v[116:117], off
	global_load_dwordx4 v[180:183], v[116:117], off offset:64
	v_add_co_u32_e32 v120, vcc, s21, v104
	s_nop 1
	v_addc_co_u32_e32 v121, vcc, 0, v105, vcc
	global_load_dwordx4 v[184:187], v[120:121], off
	global_load_dwordx4 v[188:191], v[120:121], off offset:64
	global_load_dwordx4 v[192:195], v[104:105], off offset:128
	global_load_dwordx4 v[196:199], v[106:107], off offset:128
	global_load_dwordx4 v[200:203], v[106:107], off offset:192
	global_load_dwordx4 v[204:207], v[104:105], off offset:192
	global_load_dwordx4 v[208:211], v[108:109], off offset:128
	global_load_dwordx4 v[212:215], v[108:109], off offset:192
	global_load_dwordx4 v[216:219], v[110:111], off offset:128
	global_load_dwordx4 v[220:223], v[110:111], off offset:192
	global_load_dwordx4 v[224:227], v[112:113], off offset:128
	global_load_dwordx4 v[228:231], v[112:113], off offset:192
	global_load_dwordx4 v[232:235], v[114:115], off offset:128
	global_load_dwordx4 v[236:239], v[114:115], off offset:192
	global_load_dwordx4 v[240:243], v[116:117], off offset:128
	global_load_dwordx4 v[244:247], v[116:117], off offset:192
	s_nop 9
	v_lshl_add_u32 v8, v122, 8, s0
	s_cmpk_gt_u32 s6, 0x3ff
	s_waitcnt vmcnt(28)
	v_mfma_f32_16x16x32_bf16 v[28:31], v[128:131], v[132:135], 0
	s_waitcnt vmcnt(27)
	v_mfma_f32_16x16x32_bf16 v[36:39], v[128:131], v[136:139], 0
	s_waitcnt vmcnt(24)
	v_mfma_f32_16x16x32_bf16 v[48:51], v[128:131], v[148:151], 0
	s_waitcnt vmcnt(22)
	v_mfma_f32_16x16x32_bf16 v[0:3], v[128:131], v[156:159], 0
	global_load_dwordx4 v[128:131], v[120:121], off offset:128
	s_waitcnt vmcnt(20)
	v_mfma_f32_16x16x32_bf16 v[64:67], v[168:171], v[132:135], 0
	v_mfma_f32_16x16x32_bf16 v[68:71], v[168:171], v[136:139], 0
	v_mfma_f32_16x16x32_bf16 v[72:75], v[168:171], v[148:151], 0
	v_mfma_f32_16x16x32_bf16 v[56:59], v[168:171], v[156:159], 0
	global_load_dwordx4 v[168:171], v[120:121], off offset:192
	s_waitcnt vmcnt(19)
	v_mfma_f32_16x16x32_bf16 v[84:87], v[176:179], v[132:135], 0
	v_mfma_f32_16x16x32_bf16 v[92:95], v[176:179], v[148:151], 0
	s_waitcnt vmcnt(17)
	v_mfma_f32_16x16x32_bf16 v[4:7], v[184:187], v[132:135], 0
	v_mfma_f32_16x16x32_bf16 v[24:27], v[184:187], v[148:151], 0
	v_mfma_f32_16x16x32_bf16 v[28:31], v[140:143], v[144:147], v[28:31]
	v_mfma_f32_16x16x32_bf16 v[36:39], v[140:143], v[152:155], v[36:39]
	v_mfma_f32_16x16x32_bf16 v[48:51], v[140:143], v[160:163], v[48:51]
	v_mfma_f32_16x16x32_bf16 v[0:3], v[140:143], v[164:167], v[0:3]
	v_mfma_f32_16x16x32_bf16 v[16:19], v[172:175], v[144:147], v[64:67]
	v_mfma_f32_16x16x32_bf16 v[64:67], v[172:175], v[152:155], v[68:71]
	v_mfma_f32_16x16x32_bf16 v[68:71], v[172:175], v[160:163], v[72:75]
	v_mfma_f32_16x16x32_bf16 v[56:59], v[172:175], v[164:167], v[56:59]
	v_mfma_f32_16x16x32_bf16 v[60:63], v[180:183], v[144:147], v[84:87]
	s_waitcnt vmcnt(16)
	v_mfma_f32_16x16x32_bf16 v[4:7], v[188:191], v[144:147], v[4:7]
	v_mfma_f32_16x16x32_bf16 v[20:23], v[188:191], v[160:163], v[24:27]
	s_nop 2
	s_nop 0
	v_mfma_f32_16x16x32_bf16 v[88:91], v[176:179], v[136:139], 0
	v_mfma_f32_16x16x32_bf16 v[76:79], v[176:179], v[156:159], 0
	v_mfma_f32_16x16x32_bf16 v[10:13], v[184:187], v[136:139], 0
	v_mfma_f32_16x16x32_bf16 v[40:43], v[184:187], v[156:159], 0
	v_mfma_f32_16x16x32_bf16 v[72:75], v[180:183], v[152:155], v[88:91]
	v_mfma_f32_16x16x32_bf16 v[84:87], v[180:183], v[160:163], v[92:95]
	v_mfma_f32_16x16x32_bf16 v[76:79], v[180:183], v[164:167], v[76:79]
	v_mfma_f32_16x16x32_bf16 v[10:13], v[188:191], v[152:155], v[10:13]
	v_mfma_f32_16x16x32_bf16 v[32:35], v[188:191], v[164:167], v[40:43]
	s_nop 2
	s_nop 8
	s_waitcnt vmcnt(14)
	v_mfma_f32_16x16x32_bf16 v[28:31], v[192:195], v[196:199], v[28:31]
	s_waitcnt vmcnt(11)
	v_mfma_f32_16x16x32_bf16 v[36:39], v[192:195], v[208:211], v[36:39]
	s_waitcnt vmcnt(9)
	v_mfma_f32_16x16x32_bf16 v[48:51], v[192:195], v[216:219], v[48:51]
	s_waitcnt vmcnt(7)
	v_mfma_f32_16x16x32_bf16 v[0:3], v[192:195], v[224:227], v[0:3]
	s_nop 1
	s_waitcnt vmcnt(5)
	v_mfma_f32_16x16x32_bf16 v[16:19], v[232:235], v[196:199], v[16:19]
	v_mfma_f32_16x16x32_bf16 v[64:67], v[232:235], v[208:211], v[64:67]
	v_mfma_f32_16x16x32_bf16 v[68:71], v[232:235], v[216:219], v[68:71]
	v_mfma_f32_16x16x32_bf16 v[24:27], v[232:235], v[224:227], v[56:59]
	s_nop 2
	s_nop 1
	s_nop 0
	s_nop 0
	s_waitcnt vmcnt(3)
	v_mfma_f32_16x16x32_bf16 v[60:63], v[240:243], v[196:199], v[60:63]
	v_mfma_f32_16x16x32_bf16 v[72:75], v[240:243], v[208:211], v[72:75]
	v_mfma_f32_16x16x32_bf16 v[84:87], v[240:243], v[216:219], v[84:87]
	v_mfma_f32_16x16x32_bf16 v[56:59], v[240:243], v[224:227], v[76:79]
	s_nop 2
	s_nop 0
	v_mfma_f32_16x16x32_bf16 v[28:31], v[204:207], v[200:203], v[28:31]
	s_barrier
; __device__ __forceinline__ int fresh_lane() { int l; asm volatile("v_mbcnt_lo_u32_b32 %0, -1, 0\n\tv_mbcnt_hi_u32_b32 %0, -1, %0" : "=v"(l)); return l; }
;     __device__ __forceinline__ void small8(int r, int c, const f32x4& v0, const f32x4& v1) const {
;         const float rs = rstd[r];
;         float v[8] = {v0.x * rs, v0.y * rs, v0.z * rs, v0.w * rs, v1.x * rs, v1.y * rs, v1.z * rs, v1.w * rs};
;         if (c < 1024) {
;             store8_f32(out + OFF_MK_P + (size_t)r * 1024 + c, v);
;             float ss = 0.f;
; #pragma unroll
;             for (int e = 0; e < 8; ++e) ss += v[e] * v[e];
;             ss += __shfl_xor(ss, 1); ss += __shfl_xor(ss, 2); ss += __shfl_xor(ss, 4);
;             if ((fresh_lane() & 7) == 0) atomicAdd(ssk + r * 4 + (c >> 8), ss);
;         } else store8_f32(out + OFF_MV_P + (size_t)r * 1024 + (c - 1024), v);
;     }
; template <int K, class Epi> __device__ __forceinline__ void gemm_small2_rc(const bf16_t* A, const bf16_t* Bt, int row0, int col0, int wave, int lane, const Epi& E, unsigned char* lds) {
;     ...
;     float* slab = (float*)lds + wave * 4096;
;     __syncthreads();
; #pragma unroll
;     for (int cb = 0; cb < 4; ++cb)
; #pragma unroll
;         for (int rb = 0; rb < 4; ++rb) *(f32x4*)(slab + (16 * rb + i) * 64 + 4 * ((4 * cb + q) ^ i)) = acc[cb][rb];
;     __syncthreads();
;     {
;         const int t = wave * 64 + lane, r = t >> 3, c8 = t & 7;
;         f32x4 v0 = {0.f, 0.f, 0.f, 0.f}, v1 = {0.f, 0.f, 0.f, 0.f};
; #pragma unroll
;         for (int w = 0; w < 8; ++w) { const float* sp = (const float*)lds + w * 4096 + r * 64;
;             v0 += *(const f32x4*)(sp + 4 * ((2 * c8) ^ (r & 15))); v1 += *(const f32x4*)(sp + 4 * ((2 * c8 + 1) ^ (r & 15))); }
;         E.small8(row0 + r, col0 + 8 * c8, v0, v1);
	v_mfma_f32_16x16x32_bf16 v[0:3], v[204:207], v[228:231], v[0:3]
	v_mfma_f32_16x16x32_bf16 v[36:39], v[204:207], v[212:215], v[36:39]
	s_waitcnt vmcnt(1)
	v_mfma_f32_16x16x32_bf16 v[4:7], v[128:131], v[196:199], v[4:7]
	v_mfma_f32_16x16x32_bf16 v[40:43], v[204:207], v[220:223], v[48:51]
	v_mfma_f32_16x16x32_bf16 v[48:51], v[236:239], v[212:215], v[64:67]
	s_nop 2
	v_bitop3_b32 v64, v123, v15, 15 bitop3:0x78
	v_mfma_f32_16x16x32_bf16 v[16:19], v[236:239], v[200:203], v[16:19]
	v_lshl_add_u32 v64, v64, 4, v8
	ds_write_b128 v64, v[28:31]
	ds_write_b128 v64, v[36:39] offset:4096
	ds_write_b128 v64, v[40:43] offset:8192
	ds_write_b128 v64, v[0:3] offset:12288
	v_mfma_f32_16x16x32_bf16 v[52:55], v[236:239], v[220:223], v[68:71]
	v_add_u32_e32 v0, 4, v123
	v_bitop3_b32 v36, v0, v15, 15 bitop3:0x78
	v_lshl_add_u32 v36, v36, 4, v8
	v_mfma_f32_16x16x32_bf16 v[24:27], v[236:239], v[228:231], v[24:27]
	ds_write_b128 v36, v[16:19]
	ds_write_b128 v36, v[48:51] offset:4096
	s_nop 1
	ds_write_b128 v36, v[52:55] offset:8192
	s_nop 2
	ds_write_b128 v36, v[24:27] offset:12288
	v_mfma_f32_16x16x32_bf16 v[10:13], v[128:131], v[208:211], v[10:13]
	v_add_u32_e32 v36, 8, v123
	v_bitop3_b32 v36, v36, v15, 15 bitop3:0x78
	v_lshl_add_u32 v36, v36, 4, v8
	v_mfma_f32_16x16x32_bf16 v[28:31], v[244:247], v[200:203], v[60:63]
	v_mfma_f32_16x16x32_bf16 v[0:3], v[244:247], v[212:215], v[72:75]
	v_mfma_f32_16x16x32_bf16 v[16:19], v[244:247], v[220:223], v[84:87]
	s_nop 5
	ds_write_b128 v36, v[28:31]
	v_mfma_f32_16x16x32_bf16 v[20:23], v[128:131], v[216:219], v[20:23]
	v_mfma_f32_16x16x32_bf16 v[24:27], v[244:247], v[228:231], v[56:59]
	ds_write_b128 v36, v[0:3] offset:4096
	ds_write_b128 v36, v[16:19] offset:8192
	s_nop 5
	ds_write_b128 v36, v[24:27] offset:12288
	v_mfma_f32_16x16x32_bf16 v[32:35], v[128:131], v[224:227], v[32:35]
	s_waitcnt vmcnt(0)
	v_mfma_f32_16x16x32_bf16 v[4:7], v[168:171], v[200:203], v[4:7]
	v_mfma_f32_16x16x32_bf16 v[0:3], v[168:171], v[212:215], v[10:13]
	s_nop 2
	v_add_u32_e32 v10, 12, v123
	v_bitop3_b32 v10, v10, v15, 15 bitop3:0x78
	v_lshl_add_u32 v8, v10, 4, v8
	v_mfma_f32_16x16x32_bf16 v[10:13], v[168:171], v[220:223], v[20:23]
	ds_write_b128 v8, v[4:7]
	ds_write_b128 v8, v[0:3] offset:4096
	s_nop 5
	ds_write_b128 v8, v[10:13] offset:8192
	v_mfma_f32_16x16x32_bf16 v[0:3], v[168:171], v[228:231], v[32:35]
	s_nop 7
	ds_write_b128 v8, v[0:3] offset:12288
	v_add_u32_e32 v0, s89, v15
	v_ashrrev_i32_e32 v2, 3, v0
	v_add_u32_e32 v10, s16, v2
	v_ashrrev_i32_e32 v11, 31, v10
	v_lshl_add_u64 v[0:1], v[10:11], 2, s[4:5]
	s_waitcnt lgkmcnt(0)
	s_barrier
	global_load_dword v8, v[0:1], off
	v_and_b32_e32 v15, 7, v15
	v_lshlrev_b32_e32 v0, 1, v15
	v_lshl_add_u32 v26, v2, 8, 0
	v_and_b32_e32 v1, 15, v2
	v_bitop3_b32 v2, v2, v0, 15 bitop3:0x6c
	v_lshlrev_b32_e32 v27, 4, v2
	v_add_u32_e32 v28, v26, v27
	v_bitop3_b32 v4, v0, v1, 1 bitop3:0x36
	ds_read_b128 v[0:3], v28
	v_lshlrev_b32_e32 v29, 4, v4
	v_add_u32_e32 v30, v26, v29
	ds_read_b128 v[4:7], v30
	ds_read_b128 v[16:19], v28 offset:16384
	v_lshl_or_b32 v15, v15, 3, s6
	s_waitcnt lgkmcnt(2)
	v_pk_add_f32 v[12:13], v[2:3], 0 op_sel_hi:[1,0]
	v_pk_add_f32 v[20:21], v[0:1], 0 op_sel_hi:[1,0]
	ds_read_b128 v[0:3], v30 offset:16384
	s_waitcnt lgkmcnt(2)
	v_pk_add_f32 v[22:23], v[6:7], 0 op_sel_hi:[1,0]
	v_pk_add_f32 v[24:25], v[4:5], 0 op_sel_hi:[1,0]
	ds_read_b128 v[4:7], v28 offset:32768
	s_waitcnt lgkmcnt(2)
	v_pk_add_f32 v[12:13], v[12:13], v[18:19]
	v_pk_add_f32 v[20:21], v[20:21], v[16:17]
	s_waitcnt lgkmcnt(1)
	v_pk_add_f32 v[22:23], v[22:23], v[2:3]
	v_pk_add_f32 v[24:25], v[24:25], v[0:1]
	ds_read_b128 v[0:3], v30 offset:32768
	ds_read_b128 v[16:19], v28 offset:49152
	v_add_u32_e32 v28, 0x10000, v26
	s_waitcnt lgkmcnt(2)
	v_pk_add_f32 v[12:13], v[12:13], v[6:7]
	v_pk_add_f32 v[20:21], v[20:21], v[4:5]
	ds_read_b128 v[4:7], v30 offset:49152
	s_waitcnt lgkmcnt(2)
	v_pk_add_f32 v[24:25], v[24:25], v[0:1]
	v_add_u32_e32 v0, v28, v27
	v_pk_add_f32 v[22:23], v[22:23], v[2:3]
	ds_read_b128 v[0:3], v0
	s_waitcnt lgkmcnt(2)
	v_pk_add_f32 v[12:13], v[12:13], v[18:19]
	v_pk_add_f32 v[16:17], v[20:21], v[16:17]
	s_waitcnt lgkmcnt(1)
	v_pk_add_f32 v[18:19], v[22:23], v[6:7]
	v_pk_add_f32 v[20:21], v[24:25], v[4:5]
	v_add_u32_e32 v4, v28, v29
	v_add_u32_e32 v22, 0x14000, v26
	ds_read_b128 v[4:7], v4
	s_waitcnt lgkmcnt(1)
	v_pk_add_f32 v[16:17], v[16:17], v[0:1]
	v_add_u32_e32 v0, v22, v27
	v_pk_add_f32 v[12:13], v[12:13], v[2:3]
	ds_read_b128 v[0:3], v0
	s_waitcnt lgkmcnt(1)
	v_pk_add_f32 v[20:21], v[20:21], v[4:5]
	v_add_u32_e32 v4, v22, v29
	v_add_u32_e32 v24, 0x18000, v26
	v_pk_add_f32 v[18:19], v[18:19], v[6:7]
	ds_read_b128 v[4:7], v4
	s_waitcnt lgkmcnt(1)
	v_pk_add_f32 v[16:17], v[16:17], v[0:1]
	v_add_u32_e32 v0, v24, v27
	v_pk_add_f32 v[12:13], v[12:13], v[2:3]
	ds_read_b128 v[0:3], v0
	s_waitcnt lgkmcnt(1)
	v_pk_add_f32 v[20:21], v[20:21], v[4:5]
	v_add_u32_e32 v4, v24, v29
	v_pk_add_f32 v[22:23], v[18:19], v[6:7]
	ds_read_b128 v[4:7], v4
	s_waitcnt lgkmcnt(1)
	v_pk_add_f32 v[24:25], v[16:17], v[0:1]
	v_add_u32_e32 v16, 0x1c000, v26
	v_add_u32_e32 v0, v16, v27
	v_add_u32_e32 v16, v16, v29
	v_pk_add_f32 v[12:13], v[12:13], v[2:3]
	ds_read_b128 v[0:3], v0
	ds_read_b128 v[16:19], v16
	s_waitcnt lgkmcnt(2)
	v_pk_add_f32 v[6:7], v[22:23], v[6:7]
	v_pk_add_f32 v[4:5], v[20:21], v[4:5]
	s_mov_b64 s[16:17], -1
	s_waitcnt lgkmcnt(1)
	v_pk_add_f32 v[2:3], v[12:13], v[2:3]
	v_pk_add_f32 v[0:1], v[24:25], v[0:1]
	s_waitcnt lgkmcnt(0)
	v_pk_add_f32 v[12:13], v[6:7], v[18:19]
	v_pk_add_f32 v[16:17], v[4:5], v[16:17]
	s_waitcnt vmcnt(0)
	v_pk_mul_f32 v[4:5], v[0:1], v[8:9] op_sel_hi:[1,0]
	v_pk_mul_f32 v[6:7], v[2:3], v[8:9] op_sel_hi:[1,0]
	v_pk_mul_f32 v[0:1], v[8:9], v[16:17] op_sel_hi:[0,1]
	v_pk_mul_f32 v[2:3], v[8:9], v[12:13] op_sel_hi:[0,1]
	v_lshlrev_b64 v[12:13], 12, v[10:11]
	v_lshlrev_b32_e32 v8, 2, v15
	s_cbranch_scc0 .LBB0_651
	v_readlane_b32 s24, v250, 0
	v_readlane_b32 s26, v250, 2
	v_readlane_b32 s27, v250, 3
	v_readlane_b32 s25, v250, 1
	v_readlane_b32 s28, v250, 4
	v_lshl_add_u64 v[16:17], s[26:27], 0, v[12:13]
	v_lshl_add_u64 v[16:17], v[16:17], 0, v[8:9]
	v_add_co_u32_e32 v16, vcc, 0x8a0c000, v16
	v_readlane_b32 s29, v250, 5
	s_nop 0
	v_addc_co_u32_e32 v17, vcc, 0, v17, vcc
	v_readlane_b32 s30, v250, 6
	v_readlane_b32 s31, v250, 7
	global_store_dwordx4 v[16:17], v[4:7], off
	global_store_dwordx4 v[16:17], v[0:3], off offset:16
	s_mov_b64 s[16:17], 0

; template <int K, class Epi> __device__ __forceinline__ void gemm_small2_rc(const bf16_t* A, const bf16_t* Bt, int row0, int col0, int wave, int lane, const Epi& E, unsigned char* lds) {
;     constexpr int KW = K / 8, NS = KW / 32;
;     const int i = lane & 15, q = lane >> 4;
;     const bf16_t* ap = A + (size_t)(row0 + i) * K + wave * KW + 8 * q; const bf16_t* bp = Bt + (size_t)(col0 + i) * K + wave * KW + 8 * q;
;     f32x4 acc[4][4];
; #pragma unroll
;     for (int cb = 0; cb < 4; ++cb)
; #pragma unroll
;         for (int rb = 0; rb < 4; ++rb) acc[cb][rb] = (f32x4){0.f, 0.f, 0.f, 0.f};
; #pragma unroll
;     for (int s0 = 0; s0 < NS; s0 += 4) {
;         bf16x8 a[4][4], b[4][4];
; #pragma unroll
;         for (int s = 0; s < 4; ++s) if (s0 + s < NS) {
; #pragma unroll
;             for (int x = 0; x < 4; ++x) { a[s][x] = *(const bf16x8*)(ap + (size_t)(16 * x) * K + 32 * (s0 + s)); b[s][x] = *(const bf16x8*)(bp + (size_t)(16 * x) * K + 32 * (s0 + s)); } }
; #pragma unroll
;         for (int s = 0; s < 4; ++s) if (s0 + s < NS) {
; #pragma unroll
;             for (int cb = 0; cb < 4; ++cb)
; #pragma unroll
;                 for (int rb = 0; rb < 4; ++rb) acc[cb][rb] = __builtin_amdgcn_mfma_f32_16x16x32_bf16(b[s][cb], a[s][rb], acc[cb][rb], 0, 0, 0); }
;     }
.LBB0_2911:
	s_and_b32 s7, s3, 0xffffffc0
	v_mbcnt_lo_u32_b32 v7, -1, 0
	v_mbcnt_hi_u32_b32 v7, -1, v7
	s_add_i32 s6, s7, 0x4000
	v_and_b32_e32 v126, 15, v7
	v_ashrrev_i32_e32 v127, 4, v7
	v_or_b32_e32 v2, s6, v126
	v_ashrrev_i32_e32 v3, 31, v2
	v_lshlrev_b32_e32 v8, 3, v127
	v_ashrrev_i32_e32 v9, 31, v8
	v_lshlrev_b64 v[2:3], 11, v[2:3]
	v_lshlrev_b64 v[12:13], 1, v[8:9]
	v_lshl_add_u64 v[2:3], s[4:5], 0, v[2:3]
	v_lshl_add_u64 v[2:3], v[2:3], 0, v[12:13]
	v_add_co_u32_e32 v110, vcc, s17, v2
	s_and_b32 s21, s15, 0x3c0
	s_nop 0
	v_addc_co_u32_e32 v111, vcc, 0, v3, vcc
	v_or_b32_e32 v0, s21, v126
	v_add_co_u32_e32 v112, vcc, s18, v2
	v_lshlrev_b32_e32 v0, 11, v0
	s_nop 0
	v_addc_co_u32_e32 v113, vcc, 0, v3, vcc
	v_lshl_add_u64 v[10:11], s[0:1], 0, v[0:1]
	v_add_co_u32_e32 v114, vcc, s19, v2
	v_lshl_add_u64 v[108:109], v[10:11], 0, v[12:13]
	global_load_dwordx4 v[128:131], v[108:109], off
	global_load_dwordx4 v[132:135], v[2:3], off
	global_load_dwordx4 v[136:139], v[110:111], off
	global_load_dwordx4 v[140:143], v[108:109], off offset:64
	global_load_dwordx4 v[144:147], v[2:3], off offset:64
	global_load_dwordx4 v[148:151], v[112:113], off
	global_load_dwordx4 v[152:155], v[110:111], off offset:64
	s_nop 0
	v_addc_co_u32_e32 v115, vcc, 0, v3, vcc
	global_load_dwordx4 v[156:159], v[114:115], off
	global_load_dwordx4 v[160:163], v[112:113], off offset:64
	global_load_dwordx4 v[164:167], v[114:115], off offset:64
	v_add_co_u32_e32 v116, vcc, s17, v108
	s_nop 1
	v_addc_co_u32_e32 v117, vcc, 0, v109, vcc
	global_load_dwordx4 v[168:171], v[116:117], off
	global_load_dwordx4 v[172:175], v[116:117], off offset:64
	v_add_co_u32_e32 v118, vcc, s18, v108
	s_nop 1
	v_addc_co_u32_e32 v119, vcc, 0, v109, vcc
	global_load_dwordx4 v[176:179], v[118:119], off
	global_load_dwordx4 v[180:183], v[118:119], off offset:64
	v_add_co_u32_e32 v124, vcc, s19, v108
	s_nop 1
	v_addc_co_u32_e32 v125, vcc, 0, v109, vcc
	global_load_dwordx4 v[184:187], v[124:125], off
	global_load_dwordx4 v[188:191], v[124:125], off offset:64
	global_load_dwordx4 v[192:195], v[108:109], off offset:128
	global_load_dwordx4 v[196:199], v[2:3], off offset:128
	global_load_dwordx4 v[200:203], v[2:3], off offset:192
	global_load_dwordx4 v[204:207], v[108:109], off offset:192
	global_load_dwordx4 v[208:211], v[110:111], off offset:128
	global_load_dwordx4 v[212:215], v[110:111], off offset:192
	global_load_dwordx4 v[216:219], v[112:113], off offset:128
	global_load_dwordx4 v[220:223], v[112:113], off offset:192
	global_load_dwordx4 v[224:227], v[114:115], off offset:128
	global_load_dwordx4 v[228:231], v[114:115], off offset:192
	global_load_dwordx4 v[232:235], v[116:117], off offset:128
	global_load_dwordx4 v[236:239], v[116:117], off offset:192
	global_load_dwordx4 v[240:243], v[118:119], off offset:128
	global_load_dwordx4 v[244:247], v[118:119], off offset:192
	s_nop 9
	v_lshl_add_u32 v0, v126, 8, s2
	s_waitcnt vmcnt(28)
	v_mfma_f32_16x16x32_bf16 v[32:35], v[128:131], v[132:135], 0
	s_waitcnt vmcnt(27)
	v_mfma_f32_16x16x32_bf16 v[40:43], v[128:131], v[136:139], 0
	s_waitcnt vmcnt(24)
	v_mfma_f32_16x16x32_bf16 v[52:55], v[128:131], v[148:151], 0
	s_waitcnt vmcnt(22)
	v_mfma_f32_16x16x32_bf16 v[8:11], v[128:131], v[156:159], 0
	global_load_dwordx4 v[128:131], v[124:125], off offset:128
	s_waitcnt vmcnt(20)
	v_mfma_f32_16x16x32_bf16 v[68:71], v[168:171], v[132:135], 0
	v_mfma_f32_16x16x32_bf16 v[72:75], v[168:171], v[136:139], 0
	v_mfma_f32_16x16x32_bf16 v[76:79], v[168:171], v[148:151], 0
	v_mfma_f32_16x16x32_bf16 v[60:63], v[168:171], v[156:159], 0
	global_load_dwordx4 v[168:171], v[124:125], off offset:192
	s_waitcnt vmcnt(19)
	v_mfma_f32_16x16x32_bf16 v[88:91], v[176:179], v[132:135], 0
	v_mfma_f32_16x16x32_bf16 v[96:99], v[176:179], v[148:151], 0
	s_waitcnt vmcnt(17)
	v_mfma_f32_16x16x32_bf16 v[12:15], v[184:187], v[132:135], 0
	v_mfma_f32_16x16x32_bf16 v[28:31], v[184:187], v[148:151], 0
	v_mfma_f32_16x16x32_bf16 v[32:35], v[140:143], v[144:147], v[32:35]
	v_mfma_f32_16x16x32_bf16 v[40:43], v[140:143], v[152:155], v[40:43]
	v_mfma_f32_16x16x32_bf16 v[52:55], v[140:143], v[160:163], v[52:55]
	v_mfma_f32_16x16x32_bf16 v[8:11], v[140:143], v[164:167], v[8:11]
	v_mfma_f32_16x16x32_bf16 v[20:23], v[172:175], v[144:147], v[68:71]
	v_mfma_f32_16x16x32_bf16 v[68:71], v[172:175], v[152:155], v[72:75]
	v_mfma_f32_16x16x32_bf16 v[72:75], v[172:175], v[160:163], v[76:79]
	v_mfma_f32_16x16x32_bf16 v[60:63], v[172:175], v[164:167], v[60:63]
	v_mfma_f32_16x16x32_bf16 v[64:67], v[180:183], v[144:147], v[88:91]
	s_waitcnt vmcnt(16)
	v_mfma_f32_16x16x32_bf16 v[12:15], v[188:191], v[144:147], v[12:15]
	v_mfma_f32_16x16x32_bf16 v[24:27], v[188:191], v[160:163], v[28:31]
	s_nop 2
	s_nop 0
	v_mfma_f32_16x16x32_bf16 v[92:95], v[176:179], v[136:139], 0
	v_mfma_f32_16x16x32_bf16 v[80:83], v[176:179], v[156:159], 0
	v_mfma_f32_16x16x32_bf16 v[16:19], v[184:187], v[136:139], 0
	v_mfma_f32_16x16x32_bf16 v[44:47], v[184:187], v[156:159], 0
	v_mfma_f32_16x16x32_bf16 v[76:79], v[180:183], v[152:155], v[92:95]
	v_mfma_f32_16x16x32_bf16 v[88:91], v[180:183], v[160:163], v[96:99]
	v_mfma_f32_16x16x32_bf16 v[80:83], v[180:183], v[164:167], v[80:83]
	v_mfma_f32_16x16x32_bf16 v[16:19], v[188:191], v[152:155], v[16:19]
	v_mfma_f32_16x16x32_bf16 v[36:39], v[188:191], v[164:167], v[44:47]
	s_nop 2
	s_nop 7
	s_nop 0
	s_nop 0
	s_waitcnt vmcnt(14)
	v_mfma_f32_16x16x32_bf16 v[32:35], v[192:195], v[196:199], v[32:35]
	v_bitop3_b32 v2, v127, v7, 15 bitop3:0x78
	v_lshl_add_u32 v2, v2, 4, v0
	s_waitcnt vmcnt(11)
	v_mfma_f32_16x16x32_bf16 v[40:43], v[192:195], v[208:211], v[40:43]
	s_waitcnt vmcnt(9)
	v_mfma_f32_16x16x32_bf16 v[52:55], v[192:195], v[216:219], v[52:55]
	s_waitcnt vmcnt(7)
	v_mfma_f32_16x16x32_bf16 v[8:11], v[192:195], v[224:227], v[8:11]
	s_nop 1
	s_waitcnt vmcnt(5)
	v_mfma_f32_16x16x32_bf16 v[20:23], v[232:235], v[196:199], v[20:23]
	v_mfma_f32_16x16x32_bf16 v[68:71], v[232:235], v[208:211], v[68:71]
	v_mfma_f32_16x16x32_bf16 v[72:75], v[232:235], v[216:219], v[72:75]
	v_mfma_f32_16x16x32_bf16 v[28:31], v[232:235], v[224:227], v[60:63]
	s_nop 2
	s_nop 0
	s_nop 0
	s_nop 0
	s_nop 0
	s_nop 0
	s_waitcnt vmcnt(3)
	v_mfma_f32_16x16x32_bf16 v[64:67], v[240:243], v[196:199], v[64:67]
	v_mfma_f32_16x16x32_bf16 v[76:79], v[240:243], v[208:211], v[76:79]
	v_mfma_f32_16x16x32_bf16 v[88:91], v[240:243], v[216:219], v[88:91]
	v_mfma_f32_16x16x32_bf16 v[60:63], v[240:243], v[224:227], v[80:83]
	s_nop 2
	s_nop 0
	v_mfma_f32_16x16x32_bf16 v[32:35], v[204:207], v[200:203], v[32:35]
	s_barrier
; __device__ __forceinline__ unsigned cvt_pk_bf16(float lo, float hi) { unsigned r; asm volatile("v_cvt_pk_bf16_f32 %0, %1, %2" : "=v"(r) : "v"(lo), "v"(hi)); return r; }
; __device__ __forceinline__ float bf2f(unsigned b) { return __uint_as_float(b << 16); }
;     __device__ __forceinline__ void small8(int r, int c, const f32x4& v0, const f32x4& v1) const {
;         const int rl = r - MP; f32x4 a, b;
;         if (resB) { const u32x4 w = *(const u32x4*)(resB + (size_t)r * 1024 + c);
;             a = (f32x4){bf2f(w.x & 0xffffu), bf2f(w.x >> 16), bf2f(w.y & 0xffffu), bf2f(w.y >> 16)}; b = (f32x4){bf2f(w.z & 0xffffu), bf2f(w.z >> 16), bf2f(w.w & 0xffffu), bf2f(w.w >> 16)}; }
;         else { const float* rp = resS + (size_t)rl * 1024 + c; a = *(const f32x4*)rp; b = *(const f32x4*)(rp + 4); }
;         a = a + v0; b = b + v1;
;         if (dstS) { float* dp = dstS + (size_t)rl * 1024 + c; *(f32x4*)dp = a; *(f32x4*)(dp + 4) = b; }
;         if (dstB) { u32x4 w; w.x = cvt_pk_bf16(a.x, a.y); w.y = cvt_pk_bf16(a.z, a.w); w.z = cvt_pk_bf16(b.x, b.y); w.w = cvt_pk_bf16(b.z, b.w); *(u32x4*)(dstB + (size_t)r * 1024 + c) = w; }
;         if (ss) { float s2 = (a.x * a.x + a.y * a.y) + (a.z * a.z + a.w * a.w) + (b.x * b.x + b.y * b.y) + (b.z * b.z + b.w * b.w);
;             s2 += __shfl_xor(s2, 1); s2 += __shfl_xor(s2, 2); s2 += __shfl_xor(s2, 4); if ((c & 63) == 0) atomicAdd(ss + r, s2); }
;     }
; template <int K, class Epi> __device__ __forceinline__ void gemm_small2_rc(const bf16_t* A, const bf16_t* Bt, int row0, int col0, int wave, int lane, const Epi& E, unsigned char* lds) {
;     ...
;     float* slab = (float*)lds + wave * 4096;
;     __syncthreads();
; #pragma unroll
;     for (int cb = 0; cb < 4; ++cb)
; #pragma unroll
;         for (int rb = 0; rb < 4; ++rb) *(f32x4*)(slab + (16 * rb + i) * 64 + 4 * ((4 * cb + q) ^ i)) = acc[cb][rb];
;     __syncthreads();
;     {
;         const int t = wave * 64 + lane, r = t >> 3, c8 = t & 7;
;         f32x4 v0 = {0.f, 0.f, 0.f, 0.f}, v1 = {0.f, 0.f, 0.f, 0.f};
; #pragma unroll
;         for (int w = 0; w < 8; ++w) { const float* sp = (const float*)lds + w * 4096 + r * 64;
;             v0 += *(const f32x4*)(sp + 4 * ((2 * c8) ^ (r & 15))); v1 += *(const f32x4*)(sp + 4 * ((2 * c8 + 1) ^ (r & 15))); }
;         E.small8(row0 + r, col0 + 8 * c8, v0, v1);
;     }
;     __syncthreads();
	v_mfma_f32_16x16x32_bf16 v[8:11], v[204:207], v[228:231], v[8:11]
	v_mfma_f32_16x16x32_bf16 v[40:43], v[204:207], v[212:215], v[40:43]
	s_waitcnt vmcnt(1)
	v_mfma_f32_16x16x32_bf16 v[12:15], v[128:131], v[196:199], v[12:15]
	v_mfma_f32_16x16x32_bf16 v[44:47], v[204:207], v[220:223], v[52:55]
	s_nop 1
	ds_write_b128 v2, v[32:35]
	s_nop 1
	ds_write_b128 v2, v[40:43] offset:4096
	s_nop 1
	ds_write_b128 v2, v[44:47] offset:8192
	ds_write_b128 v2, v[8:11] offset:12288
	v_mfma_f32_16x16x32_bf16 v[20:23], v[236:239], v[200:203], v[20:23]
	v_add_u32_e32 v2, 4, v127
	v_bitop3_b32 v2, v2, v7, 15 bitop3:0x78
	v_lshl_add_u32 v2, v2, 4, v0
	v_mfma_f32_16x16x32_bf16 v[56:59], v[236:239], v[220:223], v[72:75]
	v_mfma_f32_16x16x32_bf16 v[52:55], v[236:239], v[212:215], v[68:71]
	s_nop 2
	ds_write_b128 v2, v[20:23]
	s_nop 3
	ds_write_b128 v2, v[52:55] offset:4096
	v_mfma_f32_16x16x32_bf16 v[28:31], v[236:239], v[228:231], v[28:31]
	ds_write_b128 v2, v[56:59] offset:8192
	s_nop 6
	ds_write_b128 v2, v[28:31] offset:12288
	v_mfma_f32_16x16x32_bf16 v[16:19], v[128:131], v[208:211], v[16:19]
	v_add_u32_e32 v2, 8, v127
	v_bitop3_b32 v2, v2, v7, 15 bitop3:0x78
	v_lshl_add_u32 v2, v2, 4, v0
	v_mfma_f32_16x16x32_bf16 v[32:35], v[244:247], v[200:203], v[64:67]
	v_mfma_f32_16x16x32_bf16 v[8:11], v[244:247], v[212:215], v[76:79]
	v_mfma_f32_16x16x32_bf16 v[24:27], v[128:131], v[216:219], v[24:27]
	s_nop 5
	ds_write_b128 v2, v[32:35]
	v_and_b32_e32 v35, 7, v7
	v_cmp_eq_u32_e32 vcc, 0, v35
	v_mfma_f32_16x16x32_bf16 v[20:23], v[244:247], v[220:223], v[88:91]
	v_mfma_f32_16x16x32_bf16 v[28:31], v[244:247], v[228:231], v[60:63]
	ds_write_b128 v2, v[8:11] offset:4096
	s_nop 5
	ds_write_b128 v2, v[20:23] offset:8192
	ds_write_b128 v2, v[28:31] offset:12288
	v_add_u32_e32 v2, 12, v127
	v_mfma_f32_16x16x32_bf16 v[36:39], v[128:131], v[224:227], v[36:39]
	v_bitop3_b32 v2, v2, v7, 15 bitop3:0x78
	v_lshl_add_u32 v0, v2, 4, v0
	s_waitcnt vmcnt(0)
	v_mfma_f32_16x16x32_bf16 v[12:15], v[168:171], v[200:203], v[12:15]
	v_mfma_f32_16x16x32_bf16 v[8:11], v[168:171], v[212:215], v[16:19]
	v_mfma_f32_16x16x32_bf16 v[16:19], v[168:171], v[220:223], v[24:27]
	s_nop 5
	ds_write_b128 v0, v[12:15]
	ds_write_b128 v0, v[8:11] offset:4096
	ds_write_b128 v0, v[16:19] offset:8192
	v_mfma_f32_16x16x32_bf16 v[8:11], v[168:171], v[228:231], v[36:39]
	s_nop 2
	v_lshl_or_b32 v36, v35, 3, s21
	s_nop 3
	ds_write_b128 v0, v[8:11] offset:12288
	v_add_u32_e32 v0, s89, v7
	v_ashrrev_i32_e32 v34, 3, v0
	v_add_u32_e32 v2, s7, v34
	v_ashrrev_i32_e32 v3, 31, v2
	v_lshlrev_b64 v[2:3], 12, v[2:3]
	v_lshl_add_u64 v[2:3], s[38:39], 0, v[2:3]
	v_lshlrev_b32_e32 v0, 2, v36
	v_lshl_add_u64 v[2:3], v[2:3], 0, v[0:1]
	s_waitcnt lgkmcnt(0)
	s_barrier
	global_load_dwordx4 v[8:11], v[2:3], off
	global_load_dwordx4 v[12:15], v[2:3], off offset:16
	v_lshlrev_b32_e32 v2, 1, v35
	v_bitop3_b32 v7, v34, v2, 15 bitop3:0x6c
	v_lshl_add_u32 v0, v34, 8, 0
	v_lshlrev_b32_e32 v7, 4, v7
	v_add_u32_e32 v37, v0, v7
	ds_read_b128 v[16:19], v37
	v_and_b32_e32 v3, 15, v34
	v_bitop3_b32 v2, v2, v3, 1 bitop3:0x36
	v_lshlrev_b32_e32 v38, 4, v2
	v_add_u32_e32 v39, v0, v38
	ds_read_b128 v[20:23], v39
	ds_read_b128 v[24:27], v37 offset:16384
	s_waitcnt lgkmcnt(2)
	v_pk_add_f32 v[2:3], v[18:19], 0 op_sel_hi:[1,0]
	v_pk_add_f32 v[28:29], v[16:17], 0 op_sel_hi:[1,0]
	ds_read_b128 v[16:19], v39 offset:16384
	s_waitcnt lgkmcnt(2)
	v_pk_add_f32 v[30:31], v[22:23], 0 op_sel_hi:[1,0]
	v_pk_add_f32 v[32:33], v[20:21], 0 op_sel_hi:[1,0]
	ds_read_b128 v[20:23], v37 offset:32768
	s_waitcnt lgkmcnt(2)
	v_pk_add_f32 v[2:3], v[2:3], v[26:27]
	v_pk_add_f32 v[28:29], v[28:29], v[24:25]
	s_waitcnt lgkmcnt(1)
	v_pk_add_f32 v[30:31], v[30:31], v[18:19]
	v_pk_add_f32 v[32:33], v[32:33], v[16:17]
	ds_read_b128 v[16:19], v39 offset:32768
	ds_read_b128 v[24:27], v37 offset:49152
	v_add_u32_e32 v37, 0x10000, v0
	s_waitcnt lgkmcnt(2)
	v_pk_add_f32 v[2:3], v[2:3], v[22:23]
	v_pk_add_f32 v[28:29], v[28:29], v[20:21]
	ds_read_b128 v[20:23], v39 offset:49152
	s_waitcnt lgkmcnt(2)
	v_pk_add_f32 v[32:33], v[32:33], v[16:17]
	v_add_u32_e32 v16, v37, v7
	v_pk_add_f32 v[30:31], v[30:31], v[18:19]
	ds_read_b128 v[16:19], v16
	s_waitcnt lgkmcnt(2)
	v_pk_add_f32 v[2:3], v[2:3], v[26:27]
	v_pk_add_f32 v[24:25], v[28:29], v[24:25]
	s_waitcnt lgkmcnt(1)
	v_pk_add_f32 v[26:27], v[30:31], v[22:23]
	v_pk_add_f32 v[28:29], v[32:33], v[20:21]
	v_add_u32_e32 v20, v37, v38
	v_add_u32_e32 v30, 0x14000, v0
	ds_read_b128 v[20:23], v20
	s_waitcnt lgkmcnt(1)
	v_pk_add_f32 v[24:25], v[24:25], v[16:17]
	v_add_u32_e32 v16, v30, v7
	v_pk_add_f32 v[2:3], v[2:3], v[18:19]
	ds_read_b128 v[16:19], v16
	s_waitcnt lgkmcnt(1)
	v_pk_add_f32 v[28:29], v[28:29], v[20:21]
	v_add_u32_e32 v20, v30, v38
	v_add_u32_e32 v32, 0x18000, v0
	v_pk_add_f32 v[26:27], v[26:27], v[22:23]
	ds_read_b128 v[20:23], v20
	s_waitcnt lgkmcnt(1)
	v_pk_add_f32 v[24:25], v[24:25], v[16:17]
	v_add_u32_e32 v16, v32, v7
	v_pk_add_f32 v[2:3], v[2:3], v[18:19]
	ds_read_b128 v[16:19], v16
	v_add_u32_e32 v0, 0x1c000, v0
	s_waitcnt lgkmcnt(1)
	v_pk_add_f32 v[28:29], v[28:29], v[20:21]
	v_add_u32_e32 v20, v32, v38
	v_add_u32_e32 v7, v0, v7
	v_pk_add_f32 v[30:31], v[26:27], v[22:23]
	ds_read_b128 v[20:23], v20
	s_waitcnt lgkmcnt(1)
	v_pk_add_f32 v[2:3], v[2:3], v[18:19]
	v_pk_add_f32 v[32:33], v[24:25], v[16:17]
	ds_read_b128 v[16:19], v7
	v_add_u32_e32 v0, v0, v38
	ds_read_b128 v[24:27], v0
	s_waitcnt lgkmcnt(2)
	v_pk_add_f32 v[22:23], v[30:31], v[22:23]
	v_pk_add_f32 v[20:21], v[28:29], v[20:21]
	s_waitcnt lgkmcnt(1)
	v_pk_add_f32 v[2:3], v[2:3], v[18:19]
	v_pk_add_f32 v[16:17], v[32:33], v[16:17]
	s_waitcnt lgkmcnt(0)
	v_pk_add_f32 v[18:19], v[22:23], v[26:27]
	v_pk_add_f32 v[20:21], v[20:21], v[24:25]
	s_waitcnt vmcnt(1)
	v_pk_add_f32 v[22:23], v[2:3], v[10:11]
	v_pk_add_f32 v[8:9], v[16:17], v[8:9]
	v_mul_f32_e32 v2, v23, v23
	v_mul_f32_e32 v0, v9, v9
	s_waitcnt vmcnt(0)
	v_pk_add_f32 v[12:13], v[20:21], v[12:13]
	v_fmac_f32_e32 v0, v8, v8
	v_fmac_f32_e32 v2, v22, v22
	v_add_f32_e32 v0, v0, v2
	v_mul_f32_e32 v2, v13, v13
	v_pk_add_f32 v[14:15], v[18:19], v[14:15]
	v_fmac_f32_e32 v2, v12, v12
	v_add_f32_e32 v0, v2, v0
	v_mul_f32_e32 v2, v15, v15
	v_fmac_f32_e32 v2, v14, v14
	v_add_f32_e32 v0, v2, v0
	ds_bpermute_b32 v3, v4, v0
	v_add_u32_e32 v2, s6, v34
	v_cvt_pk_bf16_f32 v10, v8, v9
	v_cvt_pk_bf16_f32 v11, v22, v23
	v_cvt_pk_bf16_f32 v12, v12, v13
	s_waitcnt lgkmcnt(0)
	v_add_f32_e32 v0, v0, v3
	ds_bpermute_b32 v7, v5, v0
	v_ashrrev_i32_e32 v3, 31, v2
	v_lshlrev_b64 v[8:9], 11, v[2:3]
	v_cvt_pk_bf16_f32 v13, v14, v15
	v_lshl_add_u64 v[14:15], s[12:13], 0, v[8:9]
	s_waitcnt lgkmcnt(0)
	v_add_f32_e32 v7, v0, v7
	ds_bpermute_b32 v8, v6, v7
	v_lshlrev_b32_e32 v0, 1, v36
	v_lshl_add_u64 v[14:15], v[14:15], 0, v[0:1]
	global_store_dwordx4 v[14:15], v[10:13], off
	s_and_saveexec_b64 s[6:7], vcc
	s_cbranch_execz .LBB0_2910
	s_waitcnt lgkmcnt(0)
	v_add_f32_e32 v0, v7, v8
	v_lshl_add_u64 v[2:3], v[2:3], 2, s[10:11]
	global_atomic_add_f32 v[2:3], v0, off
	s_branch .LBB0_2910

; template <int K, class Epi> __device__ __forceinline__ void gemm_small2_rc(const bf16_t* A, const bf16_t* Bt, int row0, int col0, int wave, int lane, const Epi& E, unsigned char* lds) {
;     constexpr int KW = K / 8, NS = KW / 32;
;     const int i = lane & 15, q = lane >> 4;
;     const bf16_t* ap = A + (size_t)(row0 + i) * K + wave * KW + 8 * q; const bf16_t* bp = Bt + (size_t)(col0 + i) * K + wave * KW + 8 * q;
;     f32x4 acc[4][4];
; #pragma unroll
;     for (int cb = 0; cb < 4; ++cb)
; #pragma unroll
;         for (int rb = 0; rb < 4; ++rb) acc[cb][rb] = (f32x4){0.f, 0.f, 0.f, 0.f};
; #pragma unroll
;     for (int s0 = 0; s0 < NS; s0 += 4) {
;         bf16x8 a[4][4], b[4][4];
; #pragma unroll
;         for (int s = 0; s < 4; ++s) if (s0 + s < NS) {
; #pragma unroll
;             for (int x = 0; x < 4; ++x) { a[s][x] = *(const bf16x8*)(ap + (size_t)(16 * x) * K + 32 * (s0 + s)); b[s][x] = *(const bf16x8*)(bp + (size_t)(16 * x) * K + 32 * (s0 + s)); } }
; #pragma unroll
;         for (int s = 0; s < 4; ++s) if (s0 + s < NS) {
; #pragma unroll
;             for (int cb = 0; cb < 4; ++cb)
; #pragma unroll
;                 for (int rb = 0; rb < 4; ++rb) acc[cb][rb] = __builtin_amdgcn_mfma_f32_16x16x32_bf16(b[s][cb], a[s][rb], acc[cb][rb], 0, 0, 0); }
;     }
.LBB0_3025:
	s_and_b32 s0, s3, 0xffffffc0
	v_mbcnt_lo_u32_b32 v128, -1, 0
	v_mbcnt_hi_u32_b32 v128, -1, v128
	s_addk_i32 s0, 0x4000
	v_and_b32_e32 v129, 15, v128
	v_ashrrev_i32_e32 v130, 4, v128
	v_or_b32_e32 v6, s0, v129
	v_ashrrev_i32_e32 v7, 31, v6
	v_lshlrev_b32_e32 v2, 3, v130
	v_ashrrev_i32_e32 v3, 31, v2
	v_lshlrev_b64 v[6:7], 11, v[6:7]
	v_lshlrev_b64 v[8:9], 1, v[2:3]
	v_lshl_add_u64 v[6:7], s[16:17], 0, v[6:7]
	v_lshl_add_u64 v[110:111], v[6:7], 0, v[8:9]
	v_add_co_u32_e32 v112, vcc, s23, v110
	s_and_b32 s28, s21, 0x3c0
	s_nop 0
	v_addc_co_u32_e32 v113, vcc, 0, v111, vcc
	v_or_b32_e32 v0, s28, v129
	v_add_co_u32_e32 v114, vcc, s24, v110
	v_lshlrev_b32_e32 v0, 11, v0
	s_nop 0
	v_addc_co_u32_e32 v115, vcc, 0, v111, vcc
	v_lshl_add_u64 v[4:5], s[14:15], 0, v[0:1]
	v_add_co_u32_e32 v116, vcc, s25, v110
	v_lshl_add_u64 v[10:11], v[4:5], 0, v[8:9]
	global_load_dwordx4 v[132:135], v[10:11], off
	global_load_dwordx4 v[136:139], v[110:111], off
	global_load_dwordx4 v[140:143], v[112:113], off
	global_load_dwordx4 v[144:147], v[10:11], off offset:64
	global_load_dwordx4 v[148:151], v[110:111], off offset:64
	global_load_dwordx4 v[152:155], v[114:115], off
	global_load_dwordx4 v[156:159], v[112:113], off offset:64
	s_nop 0
	v_addc_co_u32_e32 v117, vcc, 0, v111, vcc
	global_load_dwordx4 v[160:163], v[116:117], off
	global_load_dwordx4 v[164:167], v[114:115], off offset:64
	global_load_dwordx4 v[168:171], v[116:117], off offset:64
	v_add_co_u32_e32 v118, vcc, s23, v10
	s_nop 1
	v_addc_co_u32_e32 v119, vcc, 0, v11, vcc
	global_load_dwordx4 v[172:175], v[118:119], off
	global_load_dwordx4 v[176:179], v[118:119], off offset:64
	v_add_co_u32_e32 v120, vcc, s24, v10
	s_nop 1
	v_addc_co_u32_e32 v121, vcc, 0, v11, vcc
	global_load_dwordx4 v[180:183], v[120:121], off
	global_load_dwordx4 v[184:187], v[120:121], off offset:64
	v_add_co_u32_e32 v126, vcc, s25, v10
	s_nop 1
	v_addc_co_u32_e32 v127, vcc, 0, v11, vcc
	global_load_dwordx4 v[188:191], v[126:127], off
	global_load_dwordx4 v[192:195], v[126:127], off offset:64
	global_load_dwordx4 v[196:199], v[10:11], off offset:128
	global_load_dwordx4 v[200:203], v[110:111], off offset:128
	global_load_dwordx4 v[204:207], v[110:111], off offset:192
	global_load_dwordx4 v[208:211], v[10:11], off offset:192
	global_load_dwordx4 v[212:215], v[112:113], off offset:128
	global_load_dwordx4 v[216:219], v[112:113], off offset:192
	global_load_dwordx4 v[220:223], v[114:115], off offset:128
	global_load_dwordx4 v[224:227], v[114:115], off offset:192
	global_load_dwordx4 v[228:231], v[116:117], off offset:128
	global_load_dwordx4 v[232:235], v[116:117], off offset:192
	global_load_dwordx4 v[236:239], v[118:119], off offset:128
	global_load_dwordx4 v[240:243], v[118:119], off offset:192
	global_load_dwordx4 v[244:247], v[120:121], off offset:128
	s_nop 9
	v_lshl_add_u32 v0, v129, 8, s2
	v_cmp_lt_i32_e32 vcc, v14, v15
	s_waitcnt vmcnt(27)
	v_mfma_f32_16x16x32_bf16 v[34:37], v[132:135], v[136:139], 0
	s_waitcnt vmcnt(26)
	v_mfma_f32_16x16x32_bf16 v[42:45], v[132:135], v[140:143], 0
	s_waitcnt vmcnt(23)
	v_mfma_f32_16x16x32_bf16 v[54:57], v[132:135], v[152:155], 0
	s_waitcnt vmcnt(21)
	v_mfma_f32_16x16x32_bf16 v[2:5], v[132:135], v[160:163], 0
	global_load_dwordx4 v[132:135], v[120:121], off offset:192
	s_waitcnt vmcnt(19)
	v_mfma_f32_16x16x32_bf16 v[70:73], v[172:175], v[136:139], 0
	v_mfma_f32_16x16x32_bf16 v[74:77], v[172:175], v[140:143], 0
	v_mfma_f32_16x16x32_bf16 v[78:81], v[172:175], v[152:155], 0
	v_mfma_f32_16x16x32_bf16 v[62:65], v[172:175], v[160:163], 0
	global_load_dwordx4 v[172:175], v[126:127], off offset:128
	s_waitcnt vmcnt(18)
	v_mfma_f32_16x16x32_bf16 v[90:93], v[180:183], v[136:139], 0
	v_mfma_f32_16x16x32_bf16 v[98:101], v[180:183], v[152:155], 0
	s_waitcnt vmcnt(16)
	v_mfma_f32_16x16x32_bf16 v[6:9], v[188:191], v[136:139], 0
	global_load_dwordx4 v[136:139], v[126:127], off offset:192
	v_mfma_f32_16x16x32_bf16 v[30:33], v[188:191], v[152:155], 0
	v_mfma_f32_16x16x32_bf16 v[34:37], v[144:147], v[148:151], v[34:37]
	v_mfma_f32_16x16x32_bf16 v[42:45], v[144:147], v[156:159], v[42:45]
	v_mfma_f32_16x16x32_bf16 v[54:57], v[144:147], v[164:167], v[54:57]
	v_mfma_f32_16x16x32_bf16 v[2:5], v[144:147], v[168:171], v[2:5]
	v_mfma_f32_16x16x32_bf16 v[22:25], v[176:179], v[148:151], v[70:73]
	v_mfma_f32_16x16x32_bf16 v[70:73], v[176:179], v[156:159], v[74:77]
	v_mfma_f32_16x16x32_bf16 v[74:77], v[176:179], v[164:167], v[78:81]
	v_mfma_f32_16x16x32_bf16 v[62:65], v[176:179], v[168:171], v[62:65]
	v_mfma_f32_16x16x32_bf16 v[66:69], v[184:187], v[148:151], v[90:93]
	s_waitcnt vmcnt(16)
	v_mfma_f32_16x16x32_bf16 v[6:9], v[192:195], v[148:151], v[6:9]
	v_mfma_f32_16x16x32_bf16 v[26:29], v[192:195], v[164:167], v[30:33]
	s_nop 2
	s_nop 0
	v_mfma_f32_16x16x32_bf16 v[94:97], v[180:183], v[140:143], 0
	v_mfma_f32_16x16x32_bf16 v[82:85], v[180:183], v[160:163], 0
	v_mfma_f32_16x16x32_bf16 v[18:21], v[188:191], v[140:143], 0
	v_mfma_f32_16x16x32_bf16 v[46:49], v[188:191], v[160:163], 0
	v_mfma_f32_16x16x32_bf16 v[78:81], v[184:187], v[156:159], v[94:97]
	v_mfma_f32_16x16x32_bf16 v[90:93], v[184:187], v[164:167], v[98:101]
	v_mfma_f32_16x16x32_bf16 v[82:85], v[184:187], v[168:171], v[82:85]
	v_mfma_f32_16x16x32_bf16 v[18:21], v[192:195], v[156:159], v[18:21]
	v_mfma_f32_16x16x32_bf16 v[38:41], v[192:195], v[168:171], v[46:49]
	s_nop 2
	s_nop 7
	s_nop 0
	s_nop 0
	s_waitcnt vmcnt(14)
	v_mfma_f32_16x16x32_bf16 v[34:37], v[196:199], v[200:203], v[34:37]
	v_bitop3_b32 v10, v130, v128, 15 bitop3:0x78
	v_lshl_add_u32 v10, v10, 4, v0
	s_waitcnt vmcnt(11)
	v_mfma_f32_16x16x32_bf16 v[42:45], v[196:199], v[212:215], v[42:45]
	s_waitcnt vmcnt(9)
	v_mfma_f32_16x16x32_bf16 v[54:57], v[196:199], v[220:223], v[54:57]
	s_waitcnt vmcnt(7)
	v_mfma_f32_16x16x32_bf16 v[2:5], v[196:199], v[228:231], v[2:5]
	s_nop 1
	s_waitcnt vmcnt(5)
	v_mfma_f32_16x16x32_bf16 v[22:25], v[236:239], v[200:203], v[22:25]
	v_mfma_f32_16x16x32_bf16 v[70:73], v[236:239], v[212:215], v[70:73]
	v_mfma_f32_16x16x32_bf16 v[74:77], v[236:239], v[220:223], v[74:77]
	v_mfma_f32_16x16x32_bf16 v[30:33], v[236:239], v[228:231], v[62:65]
	s_nop 2
	s_nop 0
	s_nop 0
	s_nop 0
	s_nop 0
	s_nop 0
	s_waitcnt vmcnt(3)
	v_mfma_f32_16x16x32_bf16 v[66:69], v[244:247], v[200:203], v[66:69]
	v_mfma_f32_16x16x32_bf16 v[78:81], v[244:247], v[212:215], v[78:81]
	v_mfma_f32_16x16x32_bf16 v[90:93], v[244:247], v[220:223], v[90:93]
	v_mfma_f32_16x16x32_bf16 v[62:65], v[244:247], v[228:231], v[82:85]
	s_nop 2
	s_nop 0
	v_mfma_f32_16x16x32_bf16 v[34:37], v[208:211], v[204:207], v[34:37]
	s_barrier
; __device__ __forceinline__ unsigned cvt_pk_bf16(float lo, float hi) { unsigned r; asm volatile("v_cvt_pk_bf16_f32 %0, %1, %2" : "=v"(r) : "v"(lo), "v"(hi)); return r; }
;     __device__ __forceinline__ void small8(int r, int c, const f32x4& v0, const f32x4& v1) const {
;         const float rs = __builtin_amdgcn_rsqf(ss1[r] * (1.f / 1024.f) + EPS); const f32x4 a = v0 * rs, b = v1 * rs;
;         float s2 = (a.x * a.x + a.y * a.y) + (a.z * a.z + a.w * a.w) + (b.x * b.x + b.y * b.y) + (b.z * b.z + b.w * b.w); s2 += __shfl_xor(s2, 1); s2 += __shfl_xor(s2, 2); s2 += __shfl_xor(s2, 4);
;         if ((c & 63) == 0) atomicAdd(ssq + r * 4 + (c >> 8), s2);
;         const f32x4 g0 = *(const f32x4*)(mqg + (c & 255)), g1 = *(const f32x4*)(mqg + (c & 255) + 4); const f32x4 x = a * g0, y = b * g1;
;         u32x4 w; w.x = cvt_pk_bf16(x.x, x.y); w.y = cvt_pk_bf16(x.z, x.w); w.z = cvt_pk_bf16(y.x, y.y); w.w = cvt_pk_bf16(y.z, y.w); *(u32x4*)(qmem + (size_t)r * 1024 + c) = w;
;     }
; template <int K, class Epi> __device__ __forceinline__ void gemm_small2_rc(const bf16_t* A, const bf16_t* Bt, int row0, int col0, int wave, int lane, const Epi& E, unsigned char* lds) {
;     ...
;     float* slab = (float*)lds + wave * 4096;
;     __syncthreads();
; #pragma unroll
;     for (int cb = 0; cb < 4; ++cb)
; #pragma unroll
;         for (int rb = 0; rb < 4; ++rb) *(f32x4*)(slab + (16 * rb + i) * 64 + 4 * ((4 * cb + q) ^ i)) = acc[cb][rb];
;     __syncthreads();
;     {
;         const int t = wave * 64 + lane, r = t >> 3, c8 = t & 7;
;         f32x4 v0 = {0.f, 0.f, 0.f, 0.f}, v1 = {0.f, 0.f, 0.f, 0.f};
; #pragma unroll
;         for (int w = 0; w < 8; ++w) { const float* sp = (const float*)lds + w * 4096 + r * 64;
;             v0 += *(const f32x4*)(sp + 4 * ((2 * c8) ^ (r & 15))); v1 += *(const f32x4*)(sp + 4 * ((2 * c8 + 1) ^ (r & 15))); }
;         E.small8(row0 + r, col0 + 8 * c8, v0, v1);
	v_mfma_f32_16x16x32_bf16 v[2:5], v[208:211], v[232:235], v[2:5]
	v_mfma_f32_16x16x32_bf16 v[42:45], v[208:211], v[216:219], v[42:45]
	s_waitcnt vmcnt(1)
	v_mfma_f32_16x16x32_bf16 v[6:9], v[172:175], v[200:203], v[6:9]
	v_mfma_f32_16x16x32_bf16 v[46:49], v[208:211], v[224:227], v[54:57]
	s_nop 1
	ds_write_b128 v10, v[34:37]
	s_nop 1
	ds_write_b128 v10, v[42:45] offset:4096
	s_nop 1
	ds_write_b128 v10, v[46:49] offset:8192
	ds_write_b128 v10, v[2:5] offset:12288
	v_mfma_f32_16x16x32_bf16 v[22:25], v[240:243], v[204:207], v[22:25]
	v_add_u32_e32 v2, 4, v130
	v_bitop3_b32 v10, v2, v128, 15 bitop3:0x78
	v_lshl_add_u32 v10, v10, 4, v0
	v_mfma_f32_16x16x32_bf16 v[58:61], v[240:243], v[224:227], v[74:77]
	v_mfma_f32_16x16x32_bf16 v[54:57], v[240:243], v[216:219], v[70:73]
	s_nop 2
	ds_write_b128 v10, v[22:25]
	s_nop 3
	ds_write_b128 v10, v[54:57] offset:4096
	v_mfma_f32_16x16x32_bf16 v[30:33], v[240:243], v[232:235], v[30:33]
	ds_write_b128 v10, v[58:61] offset:8192
	s_nop 6
	ds_write_b128 v10, v[30:33] offset:12288
	v_mfma_f32_16x16x32_bf16 v[18:21], v[172:175], v[212:215], v[18:21]
	v_add_u32_e32 v10, 8, v130
	v_bitop3_b32 v10, v10, v128, 15 bitop3:0x78
	v_lshl_add_u32 v10, v10, 4, v0
	v_mfma_f32_16x16x32_bf16 v[34:37], v[132:135], v[204:207], v[66:69]
	v_mfma_f32_16x16x32_bf16 v[2:5], v[132:135], v[216:219], v[78:81]
	v_mfma_f32_16x16x32_bf16 v[26:29], v[172:175], v[220:223], v[26:29]
	s_nop 5
	ds_write_b128 v10, v[34:37]
	v_mfma_f32_16x16x32_bf16 v[22:25], v[132:135], v[224:227], v[90:93]
	v_mfma_f32_16x16x32_bf16 v[30:33], v[132:135], v[232:235], v[62:65]
	ds_write_b128 v10, v[2:5] offset:4096
	s_nop 5
	ds_write_b128 v10, v[22:25] offset:8192
	ds_write_b128 v10, v[30:33] offset:12288
	v_add_u32_e32 v10, 12, v130
	v_mfma_f32_16x16x32_bf16 v[38:41], v[172:175], v[228:231], v[38:41]
	v_bitop3_b32 v10, v10, v128, 15 bitop3:0x78
	v_lshl_add_u32 v0, v10, 4, v0
	s_waitcnt vmcnt(0)
	v_mfma_f32_16x16x32_bf16 v[6:9], v[136:139], v[204:207], v[6:9]
	v_mfma_f32_16x16x32_bf16 v[2:5], v[136:139], v[216:219], v[18:21]
	v_mfma_f32_16x16x32_bf16 v[18:21], v[136:139], v[224:227], v[26:29]
	s_nop 5
	ds_write_b128 v0, v[6:9]
	ds_write_b128 v0, v[2:5] offset:4096
	ds_write_b128 v0, v[18:21] offset:8192
	v_mfma_f32_16x16x32_bf16 v[2:5], v[136:139], v[232:235], v[38:41]
	s_nop 7
	ds_write_b128 v0, v[2:5] offset:12288
	v_add_u32_e32 v0, s89, v128
	v_ashrrev_i32_e32 v6, 3, v0
	v_add_u32_e32 v2, s0, v6
	v_ashrrev_i32_e32 v3, 31, v2
	v_lshl_add_u64 v[4:5], v[2:3], 2, s[10:11]
	s_waitcnt lgkmcnt(0)
	s_barrier
	global_load_dword v30, v[4:5], off
	v_and_b32_e32 v0, 7, v128
	v_lshlrev_b32_e32 v4, 1, v0
	v_lshl_add_u32 v31, v6, 8, 0
	v_and_b32_e32 v5, 15, v6
	v_bitop3_b32 v6, v6, v4, 15 bitop3:0x6c
	v_lshlrev_b32_e32 v32, 4, v6
	v_add_u32_e32 v33, v31, v32
	v_bitop3_b32 v8, v4, v5, 1 bitop3:0x36
	ds_read_b128 v[4:7], v33
	v_lshlrev_b32_e32 v34, 4, v8
	v_add_u32_e32 v35, v31, v34
	ds_read_b128 v[8:11], v35
	ds_read_b128 v[18:21], v33 offset:16384
	s_waitcnt lgkmcnt(2)
	v_pk_add_f32 v[22:23], v[6:7], 0 op_sel_hi:[1,0]
	v_pk_add_f32 v[24:25], v[4:5], 0 op_sel_hi:[1,0]
	ds_read_b128 v[4:7], v35 offset:16384
	s_waitcnt lgkmcnt(2)
	v_pk_add_f32 v[26:27], v[10:11], 0 op_sel_hi:[1,0]
	v_pk_add_f32 v[28:29], v[8:9], 0 op_sel_hi:[1,0]
	ds_read_b128 v[8:11], v33 offset:32768
	s_waitcnt lgkmcnt(2)
	v_pk_add_f32 v[22:23], v[22:23], v[20:21]
	v_pk_add_f32 v[24:25], v[24:25], v[18:19]
	s_waitcnt lgkmcnt(1)
	v_pk_add_f32 v[26:27], v[26:27], v[6:7]
	v_pk_add_f32 v[28:29], v[28:29], v[4:5]
	ds_read_b128 v[4:7], v35 offset:32768
	ds_read_b128 v[18:21], v33 offset:49152
	v_add_u32_e32 v33, 0x10000, v31
	s_waitcnt lgkmcnt(2)
	v_pk_add_f32 v[22:23], v[22:23], v[10:11]
	v_pk_add_f32 v[24:25], v[24:25], v[8:9]
	ds_read_b128 v[8:11], v35 offset:49152
	s_waitcnt lgkmcnt(2)
	v_pk_add_f32 v[28:29], v[28:29], v[4:5]
	v_add_u32_e32 v4, v33, v32
	v_pk_add_f32 v[26:27], v[26:27], v[6:7]
	ds_read_b128 v[4:7], v4
	s_waitcnt lgkmcnt(2)
	v_pk_add_f32 v[20:21], v[22:23], v[20:21]
	v_pk_add_f32 v[18:19], v[24:25], v[18:19]
	s_waitcnt lgkmcnt(1)
	v_pk_add_f32 v[22:23], v[26:27], v[10:11]
	v_pk_add_f32 v[24:25], v[28:29], v[8:9]
	v_add_u32_e32 v8, v33, v34
	v_add_u32_e32 v26, 0x14000, v31
	ds_read_b128 v[8:11], v8
	s_waitcnt lgkmcnt(1)
	v_pk_add_f32 v[18:19], v[18:19], v[4:5]
	v_add_u32_e32 v4, v26, v32
	v_pk_add_f32 v[20:21], v[20:21], v[6:7]
	ds_read_b128 v[4:7], v4
	s_waitcnt lgkmcnt(1)
	v_pk_add_f32 v[24:25], v[24:25], v[8:9]
	v_add_u32_e32 v8, v26, v34
	v_add_u32_e32 v26, 0x18000, v31
	v_pk_add_f32 v[22:23], v[22:23], v[10:11]
	ds_read_b128 v[8:11], v8
	s_waitcnt lgkmcnt(1)
	v_pk_add_f32 v[18:19], v[18:19], v[4:5]
	v_add_u32_e32 v4, v26, v32
	v_pk_add_f32 v[20:21], v[20:21], v[6:7]
	ds_read_b128 v[4:7], v4
	s_waitcnt lgkmcnt(1)
	v_pk_add_f32 v[24:25], v[24:25], v[8:9]
	v_add_u32_e32 v8, v26, v34
	v_add_u32_e32 v26, 0x1c000, v31
	v_pk_add_f32 v[22:23], v[22:23], v[10:11]
	ds_read_b128 v[8:11], v8
	s_waitcnt lgkmcnt(1)
	v_pk_add_f32 v[18:19], v[18:19], v[4:5]
	v_add_u32_e32 v4, v26, v32
	v_pk_add_f32 v[20:21], v[20:21], v[6:7]
	ds_read_b128 v[4:7], v4
	s_waitcnt lgkmcnt(1)
	v_pk_add_f32 v[24:25], v[24:25], v[8:9]
	v_add_u32_e32 v8, v26, v34
	v_pk_add_f32 v[22:23], v[22:23], v[10:11]
	ds_read_b128 v[8:11], v8
	s_waitcnt lgkmcnt(1)
	v_pk_add_f32 v[6:7], v[20:21], v[6:7]
	v_pk_add_f32 v[4:5], v[18:19], v[4:5]
	s_waitcnt lgkmcnt(0)
	v_pk_add_f32 v[18:19], v[22:23], v[10:11]
	v_pk_add_f32 v[8:9], v[24:25], v[8:9]
	s_waitcnt vmcnt(0)
	v_fmamk_f32 v20, v30, 0x3a800000, v12
	v_rsq_f32_e32 v20, v20
	s_nop 0
	v_pk_mul_f32 v[6:7], v[6:7], v[20:21] op_sel_hi:[1,0]
	v_pk_mul_f32 v[10:11], v[4:5], v[20:21] op_sel_hi:[1,0]
	v_pk_mul_f32 v[4:5], v[18:19], v[20:21] op_sel_hi:[1,0]
	v_mul_f32_e32 v18, v11, v11
	v_mul_f32_e32 v19, v7, v7
	v_pk_mul_f32 v[8:9], v[8:9], v[20:21] op_sel_hi:[1,0]
	v_fmac_f32_e32 v18, v10, v10
	v_fmac_f32_e32 v19, v6, v6
	v_add_f32_e32 v18, v18, v19
	v_mul_f32_e32 v19, v9, v9
	v_fmac_f32_e32 v19, v8, v8
	v_add_f32_e32 v18, v19, v18
	v_mul_f32_e32 v19, v5, v5
	v_fmac_f32_e32 v19, v4, v4
	v_add_f32_e32 v18, v19, v18
	v_cndmask_b32_e32 v19, v13, v14, vcc
	v_lshlrev_b32_e32 v19, 2, v19
	ds_bpermute_b32 v19, v19, v18
	v_cmp_lt_i32_e32 vcc, v16, v15
	s_waitcnt lgkmcnt(0)
	v_add_f32_e32 v18, v18, v19
	v_cndmask_b32_e32 v19, v13, v16, vcc
	v_lshlrev_b32_e32 v19, 2, v19
	ds_bpermute_b32 v19, v19, v18
	v_cmp_lt_i32_e32 vcc, v17, v15
	s_waitcnt lgkmcnt(0)
	v_add_f32_e32 v18, v18, v19
	v_cndmask_b32_e32 v19, v13, v17, vcc
	v_lshlrev_b32_e32 v19, 2, v19
	ds_bpermute_b32 v19, v19, v18
	v_cmp_eq_u32_e32 vcc, 0, v0
	s_and_saveexec_b64 s[18:19], vcc
	s_cbranch_execz .LBB0_3024
	v_lshlrev_b32_e32 v20, 2, v2
	v_ashrrev_i32_e32 v21, 31, v20
	s_lshr_b32 s0, s28, 6
	v_lshl_add_u64 v[20:21], v[20:21], 2, s[8:9]
	s_and_b32 s0, s0, 12
	v_lshl_add_u64 v[20:21], v[20:21], 0, s[0:1]
	s_waitcnt lgkmcnt(0)
	v_add_f32_e32 v18, v18, v19
	global_atomic_add_f32 v[20:21], v18, off
	s_branch .LBB0_3024

; template <int K, class Epi> __device__ __forceinline__ void gemm_small2_rc(const bf16_t* A, const bf16_t* Bt, int row0, int col0, int wave, int lane, const Epi& E, unsigned char* lds) {
;     constexpr int KW = K / 8, NS = KW / 32;
;     const int i = lane & 15, q = lane >> 4;
;     const bf16_t* ap = A + (size_t)(row0 + i) * K + wave * KW + 8 * q; const bf16_t* bp = Bt + (size_t)(col0 + i) * K + wave * KW + 8 * q;
;     f32x4 acc[4][4];
; #pragma unroll
;     for (int cb = 0; cb < 4; ++cb)
; #pragma unroll
;         for (int rb = 0; rb < 4; ++rb) acc[cb][rb] = (f32x4){0.f, 0.f, 0.f, 0.f};
; #pragma unroll
;     for (int s0 = 0; s0 < NS; s0 += 4) {
;         bf16x8 a[4][4], b[4][4];
; #pragma unroll
;         for (int s = 0; s < 4; ++s) if (s0 + s < NS) {
; #pragma unroll
;             for (int x = 0; x < 4; ++x) { a[s][x] = *(const bf16x8*)(ap + (size_t)(16 * x) * K + 32 * (s0 + s)); b[s][x] = *(const bf16x8*)(bp + (size_t)(16 * x) * K + 32 * (s0 + s)); } }
; #pragma unroll
;         for (int s = 0; s < 4; ++s) if (s0 + s < NS) {
; #pragma unroll
;             for (int cb = 0; cb < 4; ++cb)
; #pragma unroll
;                 for (int rb = 0; rb < 4; ++rb) acc[cb][rb] = __builtin_amdgcn_mfma_f32_16x16x32_bf16(b[s][cb], a[s][rb], acc[cb][rb], 0, 0, 0); }
;     }
.LBB0_3316:
	s_and_b32 s13, s3, 0xffffffc0
	v_mbcnt_lo_u32_b32 v9, -1, 0
	v_mbcnt_hi_u32_b32 v9, -1, v9
	s_addk_i32 s13, 0x4000
	v_and_b32_e32 v128, 15, v9
	v_ashrrev_i32_e32 v129, 4, v9
	v_or_b32_e32 v2, s13, v128
	v_ashrrev_i32_e32 v3, 31, v2
	v_lshlrev_b32_e32 v10, 3, v129
	v_ashrrev_i32_e32 v11, 31, v10
	v_lshlrev_b64 v[2:3], 11, v[2:3]
	v_lshlrev_b64 v[14:15], 1, v[10:11]
	v_lshl_add_u64 v[2:3], s[10:11], 0, v[2:3]
	v_lshl_add_u64 v[2:3], v[2:3], 0, v[14:15]
	v_add_co_u32_e32 v112, vcc, s19, v2
	s_and_b32 s12, s17, 0x3c0
	s_nop 0
	v_addc_co_u32_e32 v113, vcc, 0, v3, vcc
	v_or_b32_e32 v0, s12, v128
	v_add_co_u32_e32 v114, vcc, s20, v2
	v_lshlrev_b32_e32 v0, 11, v0
	s_nop 0
	v_addc_co_u32_e32 v115, vcc, 0, v3, vcc
	v_lshl_add_u64 v[12:13], s[8:9], 0, v[0:1]
	v_add_co_u32_e32 v116, vcc, s21, v2
	v_lshl_add_u64 v[110:111], v[12:13], 0, v[14:15]
	global_load_dwordx4 v[132:135], v[110:111], off
	global_load_dwordx4 v[136:139], v[2:3], off
	global_load_dwordx4 v[140:143], v[112:113], off
	global_load_dwordx4 v[144:147], v[110:111], off offset:64
	global_load_dwordx4 v[148:151], v[2:3], off offset:64
	global_load_dwordx4 v[152:155], v[114:115], off
	global_load_dwordx4 v[156:159], v[112:113], off offset:64
	s_nop 0
	v_addc_co_u32_e32 v117, vcc, 0, v3, vcc
	global_load_dwordx4 v[160:163], v[116:117], off
	global_load_dwordx4 v[164:167], v[114:115], off offset:64
	global_load_dwordx4 v[168:171], v[116:117], off offset:64
	v_add_co_u32_e32 v118, vcc, s19, v110
	s_nop 1
	v_addc_co_u32_e32 v119, vcc, 0, v111, vcc
	global_load_dwordx4 v[172:175], v[118:119], off
	global_load_dwordx4 v[176:179], v[118:119], off offset:64
	v_add_co_u32_e32 v122, vcc, s20, v110
	s_nop 1
	v_addc_co_u32_e32 v123, vcc, 0, v111, vcc
	global_load_dwordx4 v[180:183], v[122:123], off
	global_load_dwordx4 v[184:187], v[122:123], off offset:64
	v_add_co_u32_e32 v126, vcc, s21, v110
	s_nop 1
	v_addc_co_u32_e32 v127, vcc, 0, v111, vcc
	global_load_dwordx4 v[188:191], v[126:127], off
	global_load_dwordx4 v[192:195], v[126:127], off offset:64
	global_load_dwordx4 v[196:199], v[110:111], off offset:128
	global_load_dwordx4 v[200:203], v[2:3], off offset:128
	global_load_dwordx4 v[204:207], v[2:3], off offset:192
	global_load_dwordx4 v[208:211], v[110:111], off offset:192
	global_load_dwordx4 v[212:215], v[112:113], off offset:128
	global_load_dwordx4 v[216:219], v[112:113], off offset:192
	global_load_dwordx4 v[220:223], v[114:115], off offset:128
	global_load_dwordx4 v[224:227], v[114:115], off offset:192
	global_load_dwordx4 v[228:231], v[116:117], off offset:128
	global_load_dwordx4 v[232:235], v[116:117], off offset:192
	global_load_dwordx4 v[236:239], v[118:119], off offset:128
	global_load_dwordx4 v[240:243], v[118:119], off offset:192
	global_load_dwordx4 v[244:247], v[122:123], off offset:128
	s_nop 9
	v_lshl_add_u32 v0, v128, 8, s2
	s_lshl_b32 s12, s12, 1
	v_cmp_lt_i32_e32 vcc, v5, v6
	s_waitcnt vmcnt(27)
	v_mfma_f32_16x16x32_bf16 v[34:37], v[132:135], v[136:139], 0
	s_waitcnt vmcnt(26)
	v_mfma_f32_16x16x32_bf16 v[42:45], v[132:135], v[140:143], 0
	s_waitcnt vmcnt(23)
	v_mfma_f32_16x16x32_bf16 v[54:57], v[132:135], v[152:155], 0
	s_waitcnt vmcnt(21)
	v_mfma_f32_16x16x32_bf16 v[10:13], v[132:135], v[160:163], 0
	global_load_dwordx4 v[132:135], v[122:123], off offset:192
	s_waitcnt vmcnt(19)
	v_mfma_f32_16x16x32_bf16 v[70:73], v[172:175], v[136:139], 0
	v_mfma_f32_16x16x32_bf16 v[74:77], v[172:175], v[140:143], 0
	v_mfma_f32_16x16x32_bf16 v[78:81], v[172:175], v[152:155], 0
	v_mfma_f32_16x16x32_bf16 v[62:65], v[172:175], v[160:163], 0
	global_load_dwordx4 v[172:175], v[126:127], off offset:128
	s_waitcnt vmcnt(18)
	v_mfma_f32_16x16x32_bf16 v[90:93], v[180:183], v[136:139], 0
	v_mfma_f32_16x16x32_bf16 v[98:101], v[180:183], v[152:155], 0
	s_waitcnt vmcnt(16)
	v_mfma_f32_16x16x32_bf16 v[14:17], v[188:191], v[136:139], 0
	global_load_dwordx4 v[136:139], v[126:127], off offset:192
	v_mfma_f32_16x16x32_bf16 v[30:33], v[188:191], v[152:155], 0
	v_mfma_f32_16x16x32_bf16 v[34:37], v[144:147], v[148:151], v[34:37]
	v_mfma_f32_16x16x32_bf16 v[42:45], v[144:147], v[156:159], v[42:45]
	v_mfma_f32_16x16x32_bf16 v[54:57], v[144:147], v[164:167], v[54:57]
	v_mfma_f32_16x16x32_bf16 v[10:13], v[144:147], v[168:171], v[10:13]
	v_mfma_f32_16x16x32_bf16 v[22:25], v[176:179], v[148:151], v[70:73]
	v_mfma_f32_16x16x32_bf16 v[70:73], v[176:179], v[156:159], v[74:77]
	v_mfma_f32_16x16x32_bf16 v[74:77], v[176:179], v[164:167], v[78:81]
	v_mfma_f32_16x16x32_bf16 v[62:65], v[176:179], v[168:171], v[62:65]
	v_mfma_f32_16x16x32_bf16 v[66:69], v[184:187], v[148:151], v[90:93]
	s_waitcnt vmcnt(16)
	v_mfma_f32_16x16x32_bf16 v[14:17], v[192:195], v[148:151], v[14:17]
	v_mfma_f32_16x16x32_bf16 v[26:29], v[192:195], v[164:167], v[30:33]
	s_nop 2
	s_nop 0
	v_mfma_f32_16x16x32_bf16 v[94:97], v[180:183], v[140:143], 0
	v_mfma_f32_16x16x32_bf16 v[82:85], v[180:183], v[160:163], 0
	v_mfma_f32_16x16x32_bf16 v[18:21], v[188:191], v[140:143], 0
	v_mfma_f32_16x16x32_bf16 v[46:49], v[188:191], v[160:163], 0
	v_mfma_f32_16x16x32_bf16 v[78:81], v[184:187], v[156:159], v[94:97]
	v_mfma_f32_16x16x32_bf16 v[90:93], v[184:187], v[164:167], v[98:101]
	v_mfma_f32_16x16x32_bf16 v[82:85], v[184:187], v[168:171], v[82:85]
	v_mfma_f32_16x16x32_bf16 v[18:21], v[192:195], v[156:159], v[18:21]
	v_mfma_f32_16x16x32_bf16 v[38:41], v[192:195], v[168:171], v[46:49]
	s_nop 2
	s_nop 7
	s_nop 0
	s_nop 0
	s_waitcnt vmcnt(14)
	v_mfma_f32_16x16x32_bf16 v[34:37], v[196:199], v[200:203], v[34:37]
	v_bitop3_b32 v2, v129, v9, 15 bitop3:0x78
	v_lshl_add_u32 v2, v2, 4, v0
	s_waitcnt vmcnt(11)
	v_mfma_f32_16x16x32_bf16 v[42:45], v[196:199], v[212:215], v[42:45]
	s_waitcnt vmcnt(9)
	v_mfma_f32_16x16x32_bf16 v[54:57], v[196:199], v[220:223], v[54:57]
	s_waitcnt vmcnt(7)
	v_mfma_f32_16x16x32_bf16 v[10:13], v[196:199], v[228:231], v[10:13]
	s_nop 1
	s_waitcnt vmcnt(5)
	v_mfma_f32_16x16x32_bf16 v[22:25], v[236:239], v[200:203], v[22:25]
	v_mfma_f32_16x16x32_bf16 v[70:73], v[236:239], v[212:215], v[70:73]
	v_mfma_f32_16x16x32_bf16 v[74:77], v[236:239], v[220:223], v[74:77]
	v_mfma_f32_16x16x32_bf16 v[30:33], v[236:239], v[228:231], v[62:65]
	s_nop 2
	s_nop 1
	s_nop 0
	s_nop 0
	s_waitcnt vmcnt(3)
	v_mfma_f32_16x16x32_bf16 v[66:69], v[244:247], v[200:203], v[66:69]
	v_mfma_f32_16x16x32_bf16 v[78:81], v[244:247], v[212:215], v[78:81]
	v_mfma_f32_16x16x32_bf16 v[90:93], v[244:247], v[220:223], v[90:93]
	v_mfma_f32_16x16x32_bf16 v[62:65], v[244:247], v[228:231], v[82:85]
	s_nop 2
	s_nop 0
	v_mfma_f32_16x16x32_bf16 v[34:37], v[208:211], v[204:207], v[34:37]
	s_barrier
; template <int K, class Epi> __device__ __forceinline__ void gemm_small2_rc(const bf16_t* A, const bf16_t* Bt, int row0, int col0, int wave, int lane, const Epi& E, unsigned char* lds) {
;     ...
;         for (int s = 0; s < 4; ++s) if (s0 + s < NS) {
; #pragma unroll
;             for (int cb = 0; cb < 4; ++cb)
; #pragma unroll
;                 for (int rb = 0; rb < 4; ++rb) acc[cb][rb] = __builtin_amdgcn_mfma_f32_16x16x32_bf16(b[s][cb], a[s][rb], acc[cb][rb], 0, 0, 0); }
;     }
;     float* slab = (float*)lds + wave * 4096;
;     __syncthreads();
; #pragma unroll
;     for (int cb = 0; cb < 4; ++cb)
; #pragma unroll
;         for (int rb = 0; rb < 4; ++rb) *(f32x4*)(slab + (16 * rb + i) * 64 + 4 * ((4 * cb + q) ^ i)) = acc[cb][rb];
;     __syncthreads();
	v_mfma_f32_16x16x32_bf16 v[10:13], v[208:211], v[232:235], v[10:13]
	v_mfma_f32_16x16x32_bf16 v[42:45], v[208:211], v[216:219], v[42:45]
	s_waitcnt vmcnt(1)
	v_mfma_f32_16x16x32_bf16 v[14:17], v[172:175], v[200:203], v[14:17]
	v_mfma_f32_16x16x32_bf16 v[46:49], v[208:211], v[224:227], v[54:57]
	s_nop 1
	ds_write_b128 v2, v[34:37]
	s_nop 1
	ds_write_b128 v2, v[42:45] offset:4096
	s_nop 1
	ds_write_b128 v2, v[46:49] offset:8192
	ds_write_b128 v2, v[10:13] offset:12288
	v_mfma_f32_16x16x32_bf16 v[22:25], v[240:243], v[204:207], v[22:25]
	v_add_u32_e32 v2, 4, v129
	v_bitop3_b32 v2, v2, v9, 15 bitop3:0x78
	v_lshl_add_u32 v2, v2, 4, v0
	v_mfma_f32_16x16x32_bf16 v[58:61], v[240:243], v[224:227], v[74:77]
	v_mfma_f32_16x16x32_bf16 v[54:57], v[240:243], v[216:219], v[70:73]
	s_nop 2
	ds_write_b128 v2, v[22:25]
	s_nop 3
	ds_write_b128 v2, v[54:57] offset:4096
	v_mfma_f32_16x16x32_bf16 v[30:33], v[240:243], v[232:235], v[30:33]
	ds_write_b128 v2, v[58:61] offset:8192
	s_nop 6
	ds_write_b128 v2, v[30:33] offset:12288
	v_mfma_f32_16x16x32_bf16 v[18:21], v[172:175], v[212:215], v[18:21]
	v_add_u32_e32 v2, 8, v129
	v_bitop3_b32 v2, v2, v9, 15 bitop3:0x78
	v_lshl_add_u32 v2, v2, 4, v0
	v_mfma_f32_16x16x32_bf16 v[34:37], v[132:135], v[204:207], v[66:69]
	v_mfma_f32_16x16x32_bf16 v[10:13], v[132:135], v[216:219], v[78:81]
	v_mfma_f32_16x16x32_bf16 v[26:29], v[172:175], v[220:223], v[26:29]
	s_nop 5
	ds_write_b128 v2, v[34:37]
	v_and_b32_e32 v36, 7, v9
	v_mfma_f32_16x16x32_bf16 v[22:25], v[132:135], v[224:227], v[90:93]
	v_mfma_f32_16x16x32_bf16 v[30:33], v[132:135], v[232:235], v[62:65]
	ds_write_b128 v2, v[10:13] offset:4096
	s_nop 5
	ds_write_b128 v2, v[22:25] offset:8192
	ds_write_b128 v2, v[30:33] offset:12288
	v_add_u32_e32 v2, 12, v129
	v_mfma_f32_16x16x32_bf16 v[38:41], v[172:175], v[228:231], v[38:41]
	v_bitop3_b32 v2, v2, v9, 15 bitop3:0x78
	v_lshl_add_u32 v0, v2, 4, v0
	s_waitcnt vmcnt(0)
	v_mfma_f32_16x16x32_bf16 v[14:17], v[136:139], v[204:207], v[14:17]
	v_mfma_f32_16x16x32_bf16 v[10:13], v[136:139], v[216:219], v[18:21]
	v_mfma_f32_16x16x32_bf16 v[18:21], v[136:139], v[224:227], v[26:29]
	s_nop 5
	ds_write_b128 v0, v[14:17]
	ds_write_b128 v0, v[10:13] offset:4096
	ds_write_b128 v0, v[18:21] offset:8192
	v_lshlrev_b32_e32 v15, 1, v36
	v_mfma_f32_16x16x32_bf16 v[10:13], v[136:139], v[232:235], v[38:41]
	s_nop 7
	ds_write_b128 v0, v[10:13] offset:12288
	v_add_u32_e32 v0, s89, v9
	v_ashrrev_i32_e32 v14, 3, v0
	v_add_u32_e32 v2, s13, v14
	v_ashrrev_i32_e32 v3, 31, v2
	v_lshlrev_b64 v[26:27], 11, v[2:3]
	v_lshl_add_u64 v[10:11], s[0:1], 0, v[26:27]
	v_lshl_or_b32 v0, v36, 4, s12
	v_lshl_add_u64 v[10:11], v[10:11], 0, v[0:1]
	s_waitcnt lgkmcnt(0)
	s_barrier
; __device__ __forceinline__ unsigned cvt_pk_bf16(float lo, float hi) { unsigned r; asm volatile("v_cvt_pk_bf16_f32 %0, %1, %2" : "=v"(r) : "v"(lo), "v"(hi)); return r; }
; __device__ __forceinline__ float bf2f(unsigned b) { return __uint_as_float(b << 16); }
;     __device__ __forceinline__ void small8(int r, int c, const f32x4& v0, const f32x4& v1) const {
;         const int rl = r - MP; f32x4 a, b;
;         if (resB) { const u32x4 w = *(const u32x4*)(resB + (size_t)r * 1024 + c);
;             a = (f32x4){bf2f(w.x & 0xffffu), bf2f(w.x >> 16), bf2f(w.y & 0xffffu), bf2f(w.y >> 16)}; b = (f32x4){bf2f(w.z & 0xffffu), bf2f(w.z >> 16), bf2f(w.w & 0xffffu), bf2f(w.w >> 16)}; }
;         else { const float* rp = resS + (size_t)rl * 1024 + c; a = *(const f32x4*)rp; b = *(const f32x4*)(rp + 4); }
;         a = a + v0; b = b + v1;
;         if (dstS) { float* dp = dstS + (size_t)rl * 1024 + c; *(f32x4*)dp = a; *(f32x4*)(dp + 4) = b; }
;         if (dstB) { u32x4 w; w.x = cvt_pk_bf16(a.x, a.y); w.y = cvt_pk_bf16(a.z, a.w); w.z = cvt_pk_bf16(b.x, b.y); w.w = cvt_pk_bf16(b.z, b.w); *(u32x4*)(dstB + (size_t)r * 1024 + c) = w; }
;         if (ss) { float s2 = (a.x * a.x + a.y * a.y) + (a.z * a.z + a.w * a.w) + (b.x * b.x + b.y * b.y) + (b.z * b.z + b.w * b.w);
;             s2 += __shfl_xor(s2, 1); s2 += __shfl_xor(s2, 2); s2 += __shfl_xor(s2, 4); if ((c & 63) == 0) atomicAdd(ss + r, s2); }
;     }
; template <int K, class Epi> __device__ __forceinline__ void gemm_small2_rc(const bf16_t* A, const bf16_t* Bt, int row0, int col0, int wave, int lane, const Epi& E, unsigned char* lds) {
;     ...
;     {
;         const int t = wave * 64 + lane, r = t >> 3, c8 = t & 7;
;         f32x4 v0 = {0.f, 0.f, 0.f, 0.f}, v1 = {0.f, 0.f, 0.f, 0.f};
; #pragma unroll
;         for (int w = 0; w < 8; ++w) { const float* sp = (const float*)lds + w * 4096 + r * 64;
;             v0 += *(const f32x4*)(sp + 4 * ((2 * c8) ^ (r & 15))); v1 += *(const f32x4*)(sp + 4 * ((2 * c8 + 1) ^ (r & 15))); }
;         E.small8(row0 + r, col0 + 8 * c8, v0, v1);
;     }
	global_load_dwordx4 v[10:13], v[10:11], off
	v_lshl_add_u32 v9, v14, 8, 0
	v_and_b32_e32 v16, 15, v14
	v_bitop3_b32 v14, v14, v15, 15 bitop3:0x6c
	v_lshlrev_b32_e32 v37, 4, v14
	v_add_u32_e32 v38, v9, v37
	v_bitop3_b32 v18, v15, v16, 1 bitop3:0x36
	ds_read_b128 v[14:17], v38
	v_lshlrev_b32_e32 v39, 4, v18
	v_add_u32_e32 v40, v9, v39
	ds_read_b128 v[18:21], v40
	ds_read_b128 v[22:25], v38 offset:16384
	s_waitcnt lgkmcnt(2)
	v_pk_add_f32 v[28:29], v[16:17], 0 op_sel_hi:[1,0]
	v_pk_add_f32 v[30:31], v[14:15], 0 op_sel_hi:[1,0]
	ds_read_b128 v[14:17], v40 offset:16384
	s_waitcnt lgkmcnt(2)
	v_pk_add_f32 v[32:33], v[20:21], 0 op_sel_hi:[1,0]
	v_pk_add_f32 v[34:35], v[18:19], 0 op_sel_hi:[1,0]
	ds_read_b128 v[18:21], v38 offset:32768
	s_waitcnt lgkmcnt(2)
	v_pk_add_f32 v[28:29], v[28:29], v[24:25]
	v_pk_add_f32 v[30:31], v[30:31], v[22:23]
	s_waitcnt lgkmcnt(1)
	v_pk_add_f32 v[32:33], v[32:33], v[16:17]
	v_pk_add_f32 v[34:35], v[34:35], v[14:15]
	ds_read_b128 v[14:17], v40 offset:32768
	ds_read_b128 v[22:25], v38 offset:49152
	v_add_u32_e32 v38, 0x10000, v9
	s_waitcnt lgkmcnt(2)
	v_pk_add_f32 v[28:29], v[28:29], v[20:21]
	v_pk_add_f32 v[30:31], v[30:31], v[18:19]
	ds_read_b128 v[18:21], v40 offset:49152
	s_waitcnt lgkmcnt(2)
	v_pk_add_f32 v[34:35], v[34:35], v[14:15]
	v_add_u32_e32 v14, v38, v37
	v_pk_add_f32 v[32:33], v[32:33], v[16:17]
	ds_read_b128 v[14:17], v14
	s_waitcnt lgkmcnt(2)
	v_pk_add_f32 v[24:25], v[28:29], v[24:25]
	v_pk_add_f32 v[22:23], v[30:31], v[22:23]
	s_waitcnt lgkmcnt(1)
	v_pk_add_f32 v[28:29], v[32:33], v[20:21]
	v_pk_add_f32 v[30:31], v[34:35], v[18:19]
	v_add_u32_e32 v18, v38, v39
	v_add_u32_e32 v32, 0x14000, v9
	ds_read_b128 v[18:21], v18
	s_waitcnt lgkmcnt(1)
	v_pk_add_f32 v[22:23], v[22:23], v[14:15]
	v_add_u32_e32 v14, v32, v37
	v_pk_add_f32 v[24:25], v[24:25], v[16:17]
	ds_read_b128 v[14:17], v14
	s_waitcnt lgkmcnt(1)
	v_pk_add_f32 v[30:31], v[30:31], v[18:19]
	v_add_u32_e32 v18, v32, v39
	v_add_u32_e32 v32, 0x18000, v9
	v_pk_add_f32 v[28:29], v[28:29], v[20:21]
	ds_read_b128 v[18:21], v18
	s_waitcnt lgkmcnt(1)
	v_pk_add_f32 v[22:23], v[22:23], v[14:15]
	v_add_u32_e32 v14, v32, v37
	v_pk_add_f32 v[24:25], v[24:25], v[16:17]
	ds_read_b128 v[14:17], v14
	s_waitcnt lgkmcnt(1)
	v_pk_add_f32 v[30:31], v[30:31], v[18:19]
	v_add_u32_e32 v18, v32, v39
	v_add_u32_e32 v9, 0x1c000, v9
	v_pk_add_f32 v[28:29], v[28:29], v[20:21]
	ds_read_b128 v[18:21], v18
	s_waitcnt lgkmcnt(1)
	v_pk_add_f32 v[34:35], v[22:23], v[14:15]
	v_add_u32_e32 v14, v9, v37
	v_add_u32_e32 v9, v9, v39
	v_pk_add_f32 v[32:33], v[24:25], v[16:17]
	ds_read_b128 v[14:17], v14
	ds_read_b128 v[22:25], v9
	s_waitcnt lgkmcnt(2)
	v_pk_add_f32 v[18:19], v[30:31], v[18:19]
	v_pk_add_f32 v[20:21], v[28:29], v[20:21]
	s_waitcnt lgkmcnt(1)
	v_pk_add_f32 v[16:17], v[32:33], v[16:17]
	v_pk_add_f32 v[14:15], v[34:35], v[14:15]
	s_waitcnt lgkmcnt(0)
	v_pk_add_f32 v[18:19], v[18:19], v[22:23]
	v_pk_add_f32 v[20:21], v[20:21], v[24:25]
	s_waitcnt vmcnt(0)
	v_lshlrev_b32_e32 v22, 16, v10
	v_and_b32_e32 v23, 0xffff0000, v10
	v_lshlrev_b32_e32 v10, 16, v11
	v_and_b32_e32 v11, 0xffff0000, v11
	v_lshlrev_b32_e32 v24, 16, v12
	v_and_b32_e32 v25, 0xffff0000, v12
	v_lshlrev_b32_e32 v12, 16, v13
	v_and_b32_e32 v13, 0xffff0000, v13
	v_pk_add_f32 v[10:11], v[16:17], v[10:11]
	v_pk_add_f32 v[14:15], v[14:15], v[22:23]
	v_pk_add_f32 v[16:17], v[20:21], v[12:13]
	v_mul_f32_e32 v9, v15, v15
	v_mul_f32_e32 v12, v11, v11
	v_pk_add_f32 v[18:19], v[18:19], v[24:25]
	v_fmac_f32_e32 v9, v14, v14
	v_fmac_f32_e32 v12, v10, v10
	v_add_f32_e32 v9, v9, v12
	v_mul_f32_e32 v12, v19, v19
	v_fmac_f32_e32 v12, v18, v18
	v_add_f32_e32 v9, v12, v9
	v_mul_f32_e32 v12, v17, v17
	v_fmac_f32_e32 v12, v16, v16
	v_add_f32_e32 v9, v12, v9
	v_cndmask_b32_e32 v12, v4, v5, vcc
	v_lshlrev_b32_e32 v12, 2, v12
	ds_bpermute_b32 v12, v12, v9
	v_cmp_lt_i32_e32 vcc, v7, v6
	s_waitcnt lgkmcnt(0)
	v_add_f32_e32 v9, v9, v12
	v_cndmask_b32_e32 v12, v4, v7, vcc
	v_lshlrev_b32_e32 v12, 2, v12
	ds_bpermute_b32 v20, v12, v9
	v_cmp_lt_i32_e32 vcc, v8, v6
	v_cvt_pk_bf16_f32 v12, v14, v15
	v_cvt_pk_bf16_f32 v13, v10, v11
	v_cvt_pk_bf16_f32 v14, v18, v19
	s_waitcnt lgkmcnt(0)
	v_add_f32_e32 v9, v9, v20
	v_cvt_pk_bf16_f32 v15, v16, v17
	v_cndmask_b32_e32 v10, v4, v8, vcc
	v_lshlrev_b32_e32 v10, 2, v10
	ds_bpermute_b32 v10, v10, v9
	v_lshl_add_u64 v[16:17], s[6:7], 0, v[26:27]
	v_lshl_add_u64 v[16:17], v[16:17], 0, v[0:1]
	v_cmp_eq_u32_e32 vcc, 0, v36
	global_store_dwordx4 v[16:17], v[12:15], off
	s_and_saveexec_b64 s[12:13], vcc
	s_cbranch_execz .LBB0_3315
	s_waitcnt lgkmcnt(0)
	v_add_f32_e32 v0, v9, v10
	v_lshl_add_u64 v[2:3], v[2:3], 2, s[14:15]
	global_atomic_add_f32 v[2:3], v0, off
	s_branch .LBB0_3315

; template <int K, class Epi> __device__ __forceinline__ void gemm_small2_rc(const bf16_t* A, const bf16_t* Bt, int row0, int col0, int wave, int lane, const Epi& E, unsigned char* lds) {
;     ...
; #pragma unroll
;     for (int s0 = 0; s0 < NS; s0 += 4) {
;         bf16x8 a[4][4], b[4][4];
; #pragma unroll
;         for (int s = 0; s < 4; ++s) if (s0 + s < NS) {
; #pragma unroll
;             for (int x = 0; x < 4; ++x) { a[s][x] = *(const bf16x8*)(ap + (size_t)(16 * x) * K + 32 * (s0 + s)); b[s][x] = *(const bf16x8*)(bp + (size_t)(16 * x) * K + 32 * (s0 + s)); } }
; #pragma unroll
;         for (int s = 0; s < 4; ++s) if (s0 + s < NS) {
; #pragma unroll
;             for (int cb = 0; cb < 4; ++cb)
; #pragma unroll
;                 for (int rb = 0; rb < 4; ++rb) acc[cb][rb] = __builtin_amdgcn_mfma_f32_16x16x32_bf16(b[s][cb], a[s][rb], acc[cb][rb], 0, 0, 0); }
;     }
.LBB0_3625:
	v_mbcnt_lo_u32_b32 v56, -1, 0
	v_mbcnt_hi_u32_b32 v56, -1, v56
	s_and_b32 s15, s3, 0xffffffc0
	v_ashrrev_i32_e32 v57, 4, v56
	s_and_b32 s17, s5, 0x3c0
	s_add_i32 s16, s15, 0x4000
	v_and_b32_e32 v58, 15, v56
	v_lshlrev_b32_e32 v0, 3, v57
	v_or_b32_e32 v2, s16, v58
	v_or_b32_e32 v3, s17, v58
	v_ashrrev_i32_e32 v1, 31, v0
	v_mul_u32_u24_e32 v4, 0xb00, v3
	v_mad_i64_i32 v[2:3], s[18:19], v2, s11, v[54:55]
	v_lshlrev_b64 v[0:1], 1, v[0:1]
	v_lshl_add_u64 v[22:23], v[2:3], 0, v[0:1]
	global_load_dwordx4 v[128:131], v[22:23], off
	global_load_dwordx4 v[132:135], v[22:23], off offset:64
	v_add_co_u32_e32 v24, vcc, s12, v22
	v_lshlrev_b32_e32 v52, 1, v4
	s_nop 0
	v_addc_co_u32_e32 v25, vcc, 0, v23, vcc
	v_add_co_u32_e32 v26, vcc, s13, v22
	v_lshl_add_u64 v[4:5], s[0:1], 0, v[52:53]
	s_nop 0
	v_addc_co_u32_e32 v27, vcc, 0, v23, vcc
	v_add_co_u32_e32 v28, vcc, s14, v22
	v_lshl_add_u64 v[20:21], v[4:5], 0, v[0:1]
	global_load_dwordx4 v[136:139], v[20:21], off
	global_load_dwordx4 v[140:143], v[24:25], off
	global_load_dwordx4 v[144:147], v[26:27], off
	global_load_dwordx4 v[152:155], v[22:23], off offset:640
	s_nop 0
	v_addc_co_u32_e32 v29, vcc, 0, v23, vcc
	global_load_dwordx4 v[156:159], v[28:29], off
	global_load_dwordx4 v[160:163], v[24:25], off offset:64
	global_load_dwordx4 v[164:167], v[26:27], off offset:64
	global_load_dwordx4 v[168:171], v[28:29], off offset:64
	s_nop 7
	v_add_co_u32_e32 v50, vcc, s12, v20
	s_nop 1
	v_addc_co_u32_e32 v51, vcc, 0, v21, vcc
	global_load_dwordx4 v[172:175], v[50:51], off
	global_load_dwordx4 v[176:179], v[24:25], off offset:640
	v_add_co_u32_e32 v148, vcc, s13, v20
	v_add_u32_e32 v52, s89, v56
	s_nop 0
	v_addc_co_u32_e32 v149, vcc, 0, v21, vcc
	global_load_dwordx4 v[180:183], v[148:149], off
	global_load_dwordx4 v[184:187], v[26:27], off offset:640
	v_add_co_u32_e32 v150, vcc, s14, v20
	v_and_b32_e32 v59, 7, v56
	s_nop 0
	v_addc_co_u32_e32 v151, vcc, 0, v21, vcc
	global_load_dwordx4 v[188:191], v[150:151], off
	global_load_dwordx4 v[192:195], v[28:29], off offset:640
	global_load_dwordx4 v[196:199], v[20:21], off offset:64
	global_load_dwordx4 v[200:203], v[20:21], off offset:128
	global_load_dwordx4 v[204:207], v[50:51], off offset:64
	global_load_dwordx4 v[208:211], v[50:51], off offset:128
	global_load_dwordx4 v[212:215], v[148:149], off offset:64
	global_load_dwordx4 v[216:219], v[148:149], off offset:128
	global_load_dwordx4 v[220:223], v[150:151], off offset:64
	global_load_dwordx4 v[224:227], v[150:151], off offset:128
	global_load_dwordx4 v[228:231], v[22:23], off offset:128
	global_load_dwordx4 v[232:235], v[22:23], off offset:192
	global_load_dwordx4 v[236:239], v[24:25], off offset:128
	global_load_dwordx4 v[240:243], v[24:25], off offset:192
	global_load_dwordx4 v[244:247], v[26:27], off offset:128
	v_ashrrev_i32_e32 v52, 3, v52
	s_add_i32 s84, s84, s95
	s_add_i32 s3, s3, s4
	s_add_i32 s5, s5, s10
	s_cmpk_lt_i32 s84, 0x100
	s_waitcnt vmcnt(26)
	v_mfma_f32_16x16x32_bf16 v[42:45], v[136:139], v[128:131], 0
	s_waitcnt vmcnt(25)
	v_mfma_f32_16x16x32_bf16 v[64:67], v[136:139], v[140:143], 0
	s_waitcnt vmcnt(24)
	v_mfma_f32_16x16x32_bf16 v[72:75], v[136:139], v[144:147], 0
	s_waitcnt vmcnt(22)
	v_mfma_f32_16x16x32_bf16 v[80:83], v[136:139], v[156:159], 0
	global_load_dwordx4 v[136:139], v[26:27], off offset:192
	s_nop 1
	s_waitcnt vmcnt(19)
	v_mfma_f32_16x16x32_bf16 v[84:87], v[172:175], v[128:131], 0
	v_mfma_f32_16x16x32_bf16 v[88:91], v[172:175], v[140:143], 0
	v_mfma_f32_16x16x32_bf16 v[92:95], v[172:175], v[144:147], 0
	v_mfma_f32_16x16x32_bf16 v[96:99], v[172:175], v[156:159], 0
	global_load_dwordx4 v[172:175], v[28:29], off offset:128
	s_nop 1
	s_waitcnt vmcnt(18)
	v_mfma_f32_16x16x32_bf16 v[100:103], v[180:183], v[128:131], 0
	v_mfma_f32_16x16x32_bf16 v[104:107], v[180:183], v[140:143], 0
	v_mfma_f32_16x16x32_bf16 v[108:111], v[180:183], v[144:147], 0
	v_mfma_f32_16x16x32_bf16 v[112:115], v[180:183], v[156:159], 0
	global_load_dwordx4 v[180:183], v[28:29], off offset:192
	s_nop 1
	s_waitcnt vmcnt(17)
	v_mfma_f32_16x16x32_bf16 v[30:33], v[188:191], v[128:131], 0
	global_load_dwordx4 v[128:131], v[20:21], off offset:192
	v_mfma_f32_16x16x32_bf16 v[34:37], v[188:191], v[140:143], 0
	global_load_dwordx4 v[140:143], v[20:21], off offset:256
	v_mfma_f32_16x16x32_bf16 v[38:41], v[188:191], v[144:147], 0
	global_load_dwordx4 v[144:147], v[50:51], off offset:192
	v_mfma_f32_16x16x32_bf16 v[46:49], v[188:191], v[156:159], 0
	global_load_dwordx4 v[188:191], v[50:51], off offset:256
	global_load_dwordx4 v[156:159], v[148:149], off offset:192
	s_nop 1
	s_waitcnt vmcnt(20)
	v_mfma_f32_16x16x32_bf16 v[42:45], v[196:199], v[132:135], v[42:45]
	v_mfma_f32_16x16x32_bf16 v[64:67], v[196:199], v[160:163], v[64:67]
	v_mfma_f32_16x16x32_bf16 v[72:75], v[196:199], v[164:167], v[72:75]
	v_mfma_f32_16x16x32_bf16 v[80:83], v[196:199], v[168:171], v[80:83]
	global_load_dwordx4 v[196:199], v[148:149], off offset:256
	s_nop 1
	s_waitcnt vmcnt(19)
	v_mfma_f32_16x16x32_bf16 v[84:87], v[204:207], v[132:135], v[84:87]
	v_mfma_f32_16x16x32_bf16 v[88:91], v[204:207], v[160:163], v[88:91]
	v_mfma_f32_16x16x32_bf16 v[92:95], v[204:207], v[164:167], v[92:95]
	v_mfma_f32_16x16x32_bf16 v[96:99], v[204:207], v[168:171], v[96:99]
	global_load_dwordx4 v[204:207], v[150:151], off offset:192
	s_nop 1
	s_waitcnt vmcnt(18)
	v_mfma_f32_16x16x32_bf16 v[100:103], v[212:215], v[132:135], v[100:103]
	v_mfma_f32_16x16x32_bf16 v[104:107], v[212:215], v[160:163], v[104:107]
	v_mfma_f32_16x16x32_bf16 v[108:111], v[212:215], v[164:167], v[108:111]
	v_mfma_f32_16x16x32_bf16 v[112:115], v[212:215], v[168:171], v[112:115]
	global_load_dwordx4 v[212:215], v[150:151], off offset:256
	s_nop 1
	s_waitcnt vmcnt(17)
; template <int K, class Epi> __device__ __forceinline__ void gemm_small2_rc(const bf16_t* A, const bf16_t* Bt, int row0, int col0, int wave, int lane, const Epi& E, unsigned char* lds) {
;     ...
; #pragma unroll
;     for (int s0 = 0; s0 < NS; s0 += 4) {
;         bf16x8 a[4][4], b[4][4];
; #pragma unroll
;         for (int s = 0; s < 4; ++s) if (s0 + s < NS) {
; #pragma unroll
;             for (int x = 0; x < 4; ++x) { a[s][x] = *(const bf16x8*)(ap + (size_t)(16 * x) * K + 32 * (s0 + s)); b[s][x] = *(const bf16x8*)(bp + (size_t)(16 * x) * K + 32 * (s0 + s)); } }
; #pragma unroll
;         for (int s = 0; s < 4; ++s) if (s0 + s < NS) {
; #pragma unroll
;             for (int cb = 0; cb < 4; ++cb)
; #pragma unroll
;                 for (int rb = 0; rb < 4; ++rb) acc[cb][rb] = __builtin_amdgcn_mfma_f32_16x16x32_bf16(b[s][cb], a[s][rb], acc[cb][rb], 0, 0, 0); }
;     }
	v_mfma_f32_16x16x32_bf16 v[16:19], v[220:223], v[132:135], v[30:33]
	global_load_dwordx4 v[132:135], v[22:23], off offset:256
	v_mfma_f32_16x16x32_bf16 v[30:33], v[220:223], v[160:163], v[34:37]
	global_load_dwordx4 v[160:163], v[22:23], off offset:320
	v_mfma_f32_16x16x32_bf16 v[34:37], v[220:223], v[164:167], v[38:41]
	global_load_dwordx4 v[164:167], v[24:25], off offset:256
	v_mfma_f32_16x16x32_bf16 v[38:41], v[220:223], v[168:171], v[46:49]
	global_load_dwordx4 v[220:223], v[24:25], off offset:320
	global_load_dwordx4 v[168:171], v[26:27], off offset:256
	s_nop 2
	s_nop 7
	s_waitcnt vmcnt(20)
	v_mfma_f32_16x16x32_bf16 v[42:45], v[200:203], v[228:231], v[42:45]
	s_waitcnt vmcnt(18)
	v_mfma_f32_16x16x32_bf16 v[64:67], v[200:203], v[236:239], v[64:67]
	v_mfma_f32_16x16x32_bf16 v[84:87], v[208:211], v[228:231], v[84:87]
	v_mfma_f32_16x16x32_bf16 v[88:91], v[208:211], v[236:239], v[88:91]
	v_mfma_f32_16x16x32_bf16 v[100:103], v[216:219], v[228:231], v[100:103]
	v_mfma_f32_16x16x32_bf16 v[104:107], v[216:219], v[236:239], v[104:107]
	v_mfma_f32_16x16x32_bf16 v[16:19], v[224:227], v[228:231], v[16:19]
	global_load_dwordx4 v[228:231], v[26:27], off offset:320
	v_mfma_f32_16x16x32_bf16 v[30:33], v[224:227], v[236:239], v[30:33]
	global_load_dwordx4 v[236:239], v[28:29], off offset:256
	s_nop 1
	s_waitcnt vmcnt(18)
	v_mfma_f32_16x16x32_bf16 v[72:75], v[200:203], v[244:247], v[72:75]
	s_waitcnt vmcnt(16)
	v_mfma_f32_16x16x32_bf16 v[80:83], v[200:203], v[172:175], v[80:83]
	global_load_dwordx4 v[200:203], v[28:29], off offset:320
	v_mfma_f32_16x16x32_bf16 v[92:95], v[208:211], v[244:247], v[92:95]
	v_mfma_f32_16x16x32_bf16 v[108:111], v[216:219], v[244:247], v[108:111]
	v_mfma_f32_16x16x32_bf16 v[34:37], v[224:227], v[244:247], v[34:37]
	global_load_dwordx4 v[244:247], v[20:21], off offset:320
	s_waitcnt vmcnt(16)
	v_mfma_f32_16x16x32_bf16 v[42:45], v[128:131], v[232:235], v[42:45]
	v_mfma_f32_16x16x32_bf16 v[64:67], v[128:131], v[240:243], v[64:67]
	v_mfma_f32_16x16x32_bf16 v[72:75], v[128:131], v[136:139], v[72:75]
	v_mfma_f32_16x16x32_bf16 v[46:49], v[128:131], v[180:183], v[80:83]
	global_load_dwordx4 v[128:131], v[20:21], off offset:384
	s_nop 2
	s_nop 1
	v_mfma_f32_16x16x32_bf16 v[96:99], v[208:211], v[172:175], v[96:99]
	global_load_dwordx4 v[208:211], v[50:51], off offset:320
	s_waitcnt vmcnt(16)
	v_mfma_f32_16x16x32_bf16 v[84:87], v[144:147], v[232:235], v[84:87]
	v_mfma_f32_16x16x32_bf16 v[88:91], v[144:147], v[240:243], v[88:91]
	v_mfma_f32_16x16x32_bf16 v[92:95], v[144:147], v[136:139], v[92:95]
	v_mfma_f32_16x16x32_bf16 v[80:83], v[144:147], v[180:183], v[96:99]
	global_load_dwordx4 v[144:147], v[50:51], off offset:384
	s_nop 2
	s_nop 1
	v_mfma_f32_16x16x32_bf16 v[112:115], v[216:219], v[172:175], v[112:115]
	global_load_dwordx4 v[216:219], v[148:149], off offset:320
	s_waitcnt vmcnt(16)
	v_mfma_f32_16x16x32_bf16 v[100:103], v[156:159], v[232:235], v[100:103]
	v_mfma_f32_16x16x32_bf16 v[104:107], v[156:159], v[240:243], v[104:107]
	v_mfma_f32_16x16x32_bf16 v[108:111], v[156:159], v[136:139], v[108:111]
	v_mfma_f32_16x16x32_bf16 v[96:99], v[156:159], v[180:183], v[112:115]
	global_load_dwordx4 v[156:159], v[148:149], off offset:384
	s_nop 2
	s_nop 1
	v_mfma_f32_16x16x32_bf16 v[38:41], v[224:227], v[172:175], v[38:41]
	global_load_dwordx4 v[224:227], v[150:151], off offset:320
	global_load_dwordx4 v[172:175], v[150:151], off offset:384
	s_waitcnt vmcnt(17)
	v_mfma_f32_16x16x32_bf16 v[16:19], v[204:207], v[232:235], v[16:19]
	global_load_dwordx4 v[232:235], v[22:23], off offset:384
	v_mfma_f32_16x16x32_bf16 v[30:33], v[204:207], v[240:243], v[30:33]
	global_load_dwordx4 v[240:243], v[22:23], off offset:448
	s_nop 1
	v_mfma_f32_16x16x32_bf16 v[34:37], v[204:207], v[136:139], v[34:37]
	global_load_dwordx4 v[136:139], v[24:25], off offset:384
	v_mfma_f32_16x16x32_bf16 v[38:41], v[204:207], v[180:183], v[38:41]
	global_load_dwordx4 v[204:207], v[24:25], off offset:448
	global_load_dwordx4 v[180:183], v[26:27], off offset:384
	s_nop 5
	s_waitcnt vmcnt(20)
	v_mfma_f32_16x16x32_bf16 v[42:45], v[140:143], v[132:135], v[42:45]
	s_waitcnt vmcnt(18)
	v_mfma_f32_16x16x32_bf16 v[64:67], v[140:143], v[164:167], v[64:67]
	s_waitcnt vmcnt(16)
	v_mfma_f32_16x16x32_bf16 v[72:75], v[140:143], v[168:171], v[72:75]
	s_waitcnt vmcnt(14)
	v_mfma_f32_16x16x32_bf16 v[46:49], v[140:143], v[236:239], v[46:49]
	global_load_dwordx4 v[140:143], v[26:27], off offset:448
	v_mfma_f32_16x16x32_bf16 v[68:71], v[188:191], v[132:135], v[84:87]
	v_mfma_f32_16x16x32_bf16 v[84:87], v[188:191], v[164:167], v[88:91]
	v_mfma_f32_16x16x32_bf16 v[88:91], v[188:191], v[168:171], v[92:95]
	v_mfma_f32_16x16x32_bf16 v[92:95], v[196:199], v[132:135], v[100:103]
	v_mfma_f32_16x16x32_bf16 v[100:103], v[196:199], v[164:167], v[104:107]
	v_mfma_f32_16x16x32_bf16 v[104:107], v[196:199], v[168:171], v[108:111]
	v_mfma_f32_16x16x32_bf16 v[16:19], v[212:215], v[132:135], v[16:19]
	global_load_dwordx4 v[132:135], v[28:29], off offset:384
	s_nop 0
	s_nop 0
	s_nop 0
	v_mfma_f32_16x16x32_bf16 v[30:33], v[212:215], v[164:167], v[30:33]
	global_load_dwordx4 v[164:167], v[28:29], off offset:448
	s_waitcnt vmcnt(15)
	v_mfma_f32_16x16x32_bf16 v[42:45], v[244:247], v[160:163], v[42:45]
	v_mfma_f32_16x16x32_bf16 v[64:67], v[244:247], v[220:223], v[64:67]
	v_mfma_f32_16x16x32_bf16 v[72:75], v[244:247], v[228:231], v[72:75]
	v_mfma_f32_16x16x32_bf16 v[46:49], v[244:247], v[200:203], v[46:49]
	global_load_dwordx4 v[244:247], v[20:21], off offset:448
	s_nop 1
	v_mfma_f32_16x16x32_bf16 v[80:83], v[188:191], v[236:239], v[80:83]
	global_load_dwordx4 v[188:191], v[20:21], off offset:512
	s_waitcnt vmcnt(15)
; template <int K, class Epi> __device__ __forceinline__ void gemm_small2_rc(const bf16_t* A, const bf16_t* Bt, int row0, int col0, int wave, int lane, const Epi& E, unsigned char* lds) {
;     ...
; #pragma unroll
;     for (int s0 = 0; s0 < NS; s0 += 4) {
;         bf16x8 a[4][4], b[4][4];
; #pragma unroll
;         for (int s = 0; s < 4; ++s) if (s0 + s < NS) {
; #pragma unroll
;             for (int x = 0; x < 4; ++x) { a[s][x] = *(const bf16x8*)(ap + (size_t)(16 * x) * K + 32 * (s0 + s)); b[s][x] = *(const bf16x8*)(bp + (size_t)(16 * x) * K + 32 * (s0 + s)); } }
; #pragma unroll
;         for (int s = 0; s < 4; ++s) if (s0 + s < NS) {
; #pragma unroll
;             for (int cb = 0; cb < 4; ++cb)
; #pragma unroll
;                 for (int rb = 0; rb < 4; ++rb) acc[cb][rb] = __builtin_amdgcn_mfma_f32_16x16x32_bf16(b[s][cb], a[s][rb], acc[cb][rb], 0, 0, 0); }
;     }
	v_mfma_f32_16x16x32_bf16 v[68:71], v[208:211], v[160:163], v[68:71]
	v_mfma_f32_16x16x32_bf16 v[84:87], v[208:211], v[220:223], v[84:87]
	v_mfma_f32_16x16x32_bf16 v[88:91], v[208:211], v[228:231], v[88:91]
	v_mfma_f32_16x16x32_bf16 v[60:63], v[208:211], v[200:203], v[80:83]
	global_load_dwordx4 v[208:211], v[50:51], off offset:448
	s_nop 2
	s_nop 1
	v_mfma_f32_16x16x32_bf16 v[96:99], v[196:199], v[236:239], v[96:99]
	global_load_dwordx4 v[196:199], v[50:51], off offset:512
	s_waitcnt vmcnt(15)
	v_mfma_f32_16x16x32_bf16 v[92:95], v[216:219], v[160:163], v[92:95]
	v_mfma_f32_16x16x32_bf16 v[100:103], v[216:219], v[220:223], v[100:103]
	v_mfma_f32_16x16x32_bf16 v[104:107], v[216:219], v[228:231], v[104:107]
	v_mfma_f32_16x16x32_bf16 v[80:83], v[216:219], v[200:203], v[96:99]
	global_load_dwordx4 v[216:219], v[148:149], off offset:448
	s_nop 2
	s_nop 1
	v_mfma_f32_16x16x32_bf16 v[34:37], v[212:215], v[168:171], v[34:37]
	global_load_dwordx4 v[168:171], v[148:149], off offset:512
	v_mfma_f32_16x16x32_bf16 v[38:41], v[212:215], v[236:239], v[38:41]
	global_load_dwordx4 v[212:215], v[150:151], off offset:448
	global_load_dwordx4 v[236:239], v[150:151], off offset:512
	s_waitcnt vmcnt(17)
	v_mfma_f32_16x16x32_bf16 v[16:19], v[224:227], v[160:163], v[16:19]
	global_load_dwordx4 v[160:163], v[22:23], off offset:512
	v_mfma_f32_16x16x32_bf16 v[30:33], v[224:227], v[220:223], v[30:33]
	global_load_dwordx4 v[220:223], v[22:23], off offset:576
	v_mfma_f32_16x16x32_bf16 v[34:37], v[224:227], v[228:231], v[34:37]
	global_load_dwordx4 v[228:231], v[24:25], off offset:512
	v_mfma_f32_16x16x32_bf16 v[38:41], v[224:227], v[200:203], v[38:41]
	global_load_dwordx4 v[224:227], v[24:25], off offset:576
	global_load_dwordx4 v[200:203], v[26:27], off offset:512
	s_nop 7
	s_waitcnt vmcnt(20)
	v_mfma_f32_16x16x32_bf16 v[42:45], v[128:131], v[232:235], v[42:45]
	s_waitcnt vmcnt(18)
	v_mfma_f32_16x16x32_bf16 v[64:67], v[128:131], v[136:139], v[64:67]
	s_waitcnt vmcnt(16)
	v_mfma_f32_16x16x32_bf16 v[72:75], v[128:131], v[180:183], v[72:75]
	s_waitcnt vmcnt(14)
	v_mfma_f32_16x16x32_bf16 v[46:49], v[128:131], v[132:135], v[46:49]
	global_load_dwordx4 v[128:131], v[26:27], off offset:576
	v_mfma_f32_16x16x32_bf16 v[68:71], v[144:147], v[232:235], v[68:71]
	v_mfma_f32_16x16x32_bf16 v[92:95], v[156:159], v[232:235], v[92:95]
	v_mfma_f32_16x16x32_bf16 v[16:19], v[172:175], v[232:235], v[16:19]
	global_load_dwordx4 v[232:235], v[28:29], off offset:512
	s_nop 1
	v_mfma_f32_16x16x32_bf16 v[84:87], v[144:147], v[136:139], v[84:87]
	v_mfma_f32_16x16x32_bf16 v[88:91], v[144:147], v[180:183], v[88:91]
	v_mfma_f32_16x16x32_bf16 v[60:63], v[144:147], v[132:135], v[60:63]
	global_load_dwordx4 v[144:147], v[28:29], off offset:576
	s_waitcnt vmcnt(15)
	v_mfma_f32_16x16x32_bf16 v[42:45], v[244:247], v[240:243], v[42:45]
	v_mfma_f32_16x16x32_bf16 v[64:67], v[244:247], v[204:207], v[64:67]
	v_mfma_f32_16x16x32_bf16 v[72:75], v[244:247], v[140:143], v[72:75]
	v_mfma_f32_16x16x32_bf16 v[46:49], v[244:247], v[164:167], v[46:49]
	global_load_dwordx4 v[244:247], v[20:21], off offset:576
	s_nop 1
	v_mfma_f32_16x16x32_bf16 v[100:103], v[156:159], v[136:139], v[100:103]
	v_mfma_f32_16x16x32_bf16 v[104:107], v[156:159], v[180:183], v[104:107]
	v_mfma_f32_16x16x32_bf16 v[80:83], v[156:159], v[132:135], v[80:83]
	global_load_dwordx4 v[156:159], v[20:21], off offset:640
	s_waitcnt vmcnt(15)
	v_mfma_f32_16x16x32_bf16 v[68:71], v[208:211], v[240:243], v[68:71]
	v_mfma_f32_16x16x32_bf16 v[84:87], v[208:211], v[204:207], v[84:87]
	v_mfma_f32_16x16x32_bf16 v[88:91], v[208:211], v[140:143], v[88:91]
	v_mfma_f32_16x16x32_bf16 v[60:63], v[208:211], v[164:167], v[60:63]
	global_load_dwordx4 v[208:211], v[50:51], off offset:576
	s_nop 1
	v_mfma_f32_16x16x32_bf16 v[30:33], v[172:175], v[136:139], v[30:33]
	global_load_dwordx4 v[136:139], v[50:51], off offset:640
	v_mfma_f32_16x16x32_bf16 v[34:37], v[172:175], v[180:183], v[34:37]
	global_load_dwordx4 v[180:183], v[148:149], off offset:576
	v_mfma_f32_16x16x32_bf16 v[38:41], v[172:175], v[132:135], v[38:41]
	global_load_dwordx4 v[172:175], v[148:149], off offset:640
	global_load_dwordx4 v[132:135], v[150:151], off offset:576
	s_waitcnt vmcnt(18)
	v_mfma_f32_16x16x32_bf16 v[92:95], v[216:219], v[240:243], v[92:95]
	v_mfma_f32_16x16x32_bf16 v[100:103], v[216:219], v[204:207], v[100:103]
	v_mfma_f32_16x16x32_bf16 v[104:107], v[216:219], v[140:143], v[104:107]
	v_mfma_f32_16x16x32_bf16 v[76:79], v[216:219], v[164:167], v[80:83]
	global_load_dwordx4 v[216:219], v[150:151], off offset:640
	s_nop 2
	s_nop 1
	s_waitcnt vmcnt(17)
	v_mfma_f32_16x16x32_bf16 v[16:19], v[212:215], v[240:243], v[16:19]
	v_mfma_f32_16x16x32_bf16 v[30:33], v[212:215], v[204:207], v[30:33]
	v_mfma_f32_16x16x32_bf16 v[34:37], v[212:215], v[140:143], v[34:37]
	v_mfma_f32_16x16x32_bf16 v[38:41], v[212:215], v[164:167], v[38:41]
	s_nop 2
	s_nop 0
	s_nop 0
	s_nop 0
	s_nop 2
	s_nop 0
	s_nop 0
	s_waitcnt vmcnt(15)
	v_mfma_f32_16x16x32_bf16 v[42:45], v[188:191], v[160:163], v[42:45]
	v_mfma_f32_16x16x32_bf16 v[68:71], v[196:199], v[160:163], v[68:71]
	s_waitcnt vmcnt(13)
	v_mfma_f32_16x16x32_bf16 v[84:87], v[196:199], v[228:231], v[84:87]
	s_waitcnt vmcnt(11)
	v_mfma_f32_16x16x32_bf16 v[88:91], v[196:199], v[200:203], v[88:91]
	s_waitcnt vmcnt(9)
; template <int K, class Epi> __device__ __forceinline__ void gemm_small2_rc(const bf16_t* A, const bf16_t* Bt, int row0, int col0, int wave, int lane, const Epi& E, unsigned char* lds) {
;     ...
; #pragma unroll
;     for (int s0 = 0; s0 < NS; s0 += 4) {
;         bf16x8 a[4][4], b[4][4];
; #pragma unroll
;         for (int s = 0; s < 4; ++s) if (s0 + s < NS) {
; #pragma unroll
;             for (int x = 0; x < 4; ++x) { a[s][x] = *(const bf16x8*)(ap + (size_t)(16 * x) * K + 32 * (s0 + s)); b[s][x] = *(const bf16x8*)(bp + (size_t)(16 * x) * K + 32 * (s0 + s)); } }
; #pragma unroll
;         for (int s = 0; s < 4; ++s) if (s0 + s < NS) {
; #pragma unroll
;             for (int cb = 0; cb < 4; ++cb)
; #pragma unroll
;                 for (int rb = 0; rb < 4; ++rb) acc[cb][rb] = __builtin_amdgcn_mfma_f32_16x16x32_bf16(b[s][cb], a[s][rb], acc[cb][rb], 0, 0, 0); }
;     }
;     float* slab = (float*)lds + wave * 4096;
;     __syncthreads();
; #pragma unroll
;     for (int cb = 0; cb < 4; ++cb)
; #pragma unroll
;         for (int rb = 0; rb < 4; ++rb) *(f32x4*)(slab + (16 * rb + i) * 64 + 4 * ((4 * cb + q) ^ i)) = acc[cb][rb];
	v_mfma_f32_16x16x32_bf16 v[60:63], v[196:199], v[232:235], v[60:63]
	v_mfma_f32_16x16x32_bf16 v[92:95], v[168:171], v[160:163], v[92:95]
	v_mfma_f32_16x16x32_bf16 v[80:83], v[236:239], v[160:163], v[16:19]
	s_nop 2
	s_nop 1
	v_mfma_f32_16x16x32_bf16 v[64:67], v[188:191], v[228:231], v[64:67]
	v_mfma_f32_16x16x32_bf16 v[72:75], v[188:191], v[200:203], v[72:75]
	v_mfma_f32_16x16x32_bf16 v[46:49], v[188:191], v[232:235], v[46:49]
	v_mfma_f32_16x16x32_bf16 v[100:103], v[168:171], v[228:231], v[100:103]
	v_mfma_f32_16x16x32_bf16 v[104:107], v[168:171], v[200:203], v[104:107]
	v_mfma_f32_16x16x32_bf16 v[76:79], v[168:171], v[232:235], v[76:79]
	v_mfma_f32_16x16x32_bf16 v[30:33], v[236:239], v[228:231], v[30:33]
	v_mfma_f32_16x16x32_bf16 v[34:37], v[236:239], v[200:203], v[34:37]
	v_mfma_f32_16x16x32_bf16 v[108:111], v[236:239], v[232:235], v[38:41]
	s_waitcnt vmcnt(7)
	v_mfma_f32_16x16x32_bf16 v[116:119], v[244:247], v[220:223], v[42:45]
	v_mfma_f32_16x16x32_bf16 v[64:67], v[244:247], v[224:227], v[64:67]
	v_mfma_f32_16x16x32_bf16 v[72:75], v[244:247], v[128:131], v[72:75]
	v_mfma_f32_16x16x32_bf16 v[120:123], v[244:247], v[144:147], v[46:49]
	s_nop 1
	s_waitcnt vmcnt(5)
	v_mfma_f32_16x16x32_bf16 v[68:71], v[208:211], v[220:223], v[68:71]
	v_mfma_f32_16x16x32_bf16 v[84:87], v[208:211], v[224:227], v[84:87]
	v_mfma_f32_16x16x32_bf16 v[88:91], v[208:211], v[128:131], v[88:91]
	v_mfma_f32_16x16x32_bf16 v[60:63], v[208:211], v[144:147], v[60:63]
	s_nop 2
	s_waitcnt vmcnt(3)
	v_mfma_f32_16x16x32_bf16 v[92:95], v[180:183], v[220:223], v[92:95]
	v_mfma_f32_16x16x32_bf16 v[100:103], v[180:183], v[224:227], v[100:103]
	v_mfma_f32_16x16x32_bf16 v[104:107], v[180:183], v[128:131], v[104:107]
	v_mfma_f32_16x16x32_bf16 v[76:79], v[180:183], v[144:147], v[76:79]
	s_nop 0
	s_barrier
	s_waitcnt vmcnt(1)
	v_mfma_f32_16x16x32_bf16 v[48:51], v[132:135], v[220:223], v[80:83]
	v_lshl_add_u32 v96, v58, 8, s2
	v_bitop3_b32 v58, v57, v56, 15 bitop3:0x78
	v_add_u32_e32 v97, 4, v57
	v_mfma_f32_16x16x32_bf16 v[44:47], v[132:135], v[224:227], v[30:33]
	v_add_u32_e32 v98, 8, v57
	v_add_u32_e32 v57, 12, v57
	v_lshlrev_b32_e32 v99, 1, v59
	v_mfma_f32_16x16x32_bf16 v[20:23], v[132:135], v[144:147], v[108:111]
	v_bitop3_b32 v57, v57, v56, 15 bitop3:0x78
	s_nop 1
	v_lshl_or_b32 v108, v59, 3, s17
	v_lshl_add_u32 v109, v58, 4, v96
	v_mfma_f32_16x16x32_bf16 v[58:61], v[136:139], v[192:195], v[60:63]
	v_and_b32_e32 v110, 15, v52
	v_bitop3_b32 v111, v52, v99, 15 bitop3:0x6c
	s_nop 0
	v_bitop3_b32 v63, v97, v56, 15 bitop3:0x78
	v_bitop3_b32 v97, v98, v56, 15 bitop3:0x78
	v_add_u32_e32 v56, s16, v52
	v_mfma_f32_16x16x32_bf16 v[36:39], v[132:135], v[128:131], v[34:37]
	v_lshl_add_u32 v63, v63, 4, v96
	v_lshl_add_u32 v97, v97, 4, v96
	v_lshl_add_u32 v96, v57, 4, v96
	v_mfma_f32_16x16x32_bf16 v[24:27], v[156:159], v[152:155], v[116:119]
	v_ashrrev_i32_e32 v57, 31, v56
	v_lshl_add_u32 v98, v52, 8, 0
	v_add_u32_e32 v62, s15, v52
	v_mfma_f32_16x16x32_bf16 v[28:31], v[156:159], v[176:179], v[64:67]
	v_lshlrev_b32_e32 v52, 1, v108
	v_mfma_f32_16x16x32_bf16 v[32:35], v[156:159], v[184:187], v[72:75]
	v_mfma_f32_16x16x32_bf16 v[68:71], v[136:139], v[152:155], v[68:71]
	v_mfma_f32_16x16x32_bf16 v[72:75], v[136:139], v[176:179], v[84:87]
	v_mfma_f32_16x16x32_bf16 v[84:87], v[172:175], v[152:155], v[92:95]
	s_waitcnt vmcnt(0)
	v_mfma_f32_16x16x32_bf16 v[0:3], v[216:219], v[152:155], v[48:51]
	s_nop 2
	v_lshlrev_b64 v[48:49], 11, v[56:57]
	v_add_u32_e32 v50, 0x18000, v98
	v_mfma_f32_16x16x32_bf16 v[80:83], v[136:139], v[184:187], v[88:91]
	v_mfma_f32_16x16x32_bf16 v[88:91], v[172:175], v[176:179], v[100:103]
	v_mfma_f32_16x16x32_bf16 v[4:7], v[216:219], v[176:179], v[44:47]
	s_nop 1
	v_lshlrev_b32_e32 v100, 4, v111
	v_add_u32_e32 v56, v50, v100
	v_lshl_add_u64 v[44:45], s[6:7], 0, v[48:49]
	v_mfma_f32_16x16x32_bf16 v[64:67], v[156:159], v[192:195], v[120:123]
	v_lshl_add_u64 v[44:45], v[44:45], 0, v[52:53]
	v_lshlrev_b32_e32 v52, 2, v108
	v_mfma_f32_16x16x32_bf16 v[92:95], v[172:175], v[184:187], v[104:107]
	v_mfma_f32_16x16x32_bf16 v[40:43], v[172:175], v[192:195], v[76:79]
	v_mfma_f32_16x16x32_bf16 v[8:11], v[216:219], v[184:187], v[36:39]
	s_nop 1
	v_bitop3_b32 v76, v99, v110, 1 bitop3:0x36
	v_add_u32_e32 v77, 0x10000, v98
	v_add_u32_e32 v78, 0x14000, v98
	v_mfma_f32_16x16x32_bf16 v[12:15], v[216:219], v[192:195], v[20:23]
	ds_write_b128 v109, v[24:27]
	ds_write_b128 v109, v[28:31] offset:4096
	ds_write_b128 v109, v[32:35] offset:8192
	ds_write_b128 v109, v[64:67] offset:12288
	ds_write_b128 v63, v[68:71]
	ds_write_b128 v63, v[72:75] offset:4096
	ds_write_b128 v63, v[80:83] offset:8192
	ds_write_b128 v63, v[58:61] offset:12288
	ds_write_b128 v97, v[84:87]
	ds_write_b128 v97, v[88:91] offset:4096
	ds_write_b128 v97, v[92:95] offset:8192
	ds_write_b128 v97, v[40:43] offset:12288
	ds_write_b128 v96, v[0:3]
	ds_write_b128 v96, v[4:7] offset:4096
	ds_write_b128 v96, v[8:11] offset:8192
	ds_write_b128 v96, v[12:15] offset:12288
	s_waitcnt lgkmcnt(0)
	s_barrier
; __device__ __forceinline__ unsigned cvt_pk_bf16(float lo, float hi) { unsigned r; asm volatile("v_cvt_pk_bf16_f32 %0, %1, %2" : "=v"(r) : "v"(lo), "v"(hi)); return r; }
; __device__ __forceinline__ float bf2f(unsigned b) { return __uint_as_float(b << 16); }
;     __device__ __forceinline__ void small8(int r, int c, const f32x4& v0, const f32x4& v1) const {
;         const int rl = r - MP; f32x4 a, b;
;         if (resB) { const u32x4 w = *(const u32x4*)(resB + (size_t)r * 1024 + c);
;             a = (f32x4){bf2f(w.x & 0xffffu), bf2f(w.x >> 16), bf2f(w.y & 0xffffu), bf2f(w.y >> 16)}; b = (f32x4){bf2f(w.z & 0xffffu), bf2f(w.z >> 16), bf2f(w.w & 0xffffu), bf2f(w.w >> 16)}; }
;         else { const float* rp = resS + (size_t)rl * 1024 + c; a = *(const f32x4*)rp; b = *(const f32x4*)(rp + 4); }
;         a = a + v0; b = b + v1;
;         if (dstS) { float* dp = dstS + (size_t)rl * 1024 + c; *(f32x4*)dp = a; *(f32x4*)(dp + 4) = b; }
;         if (dstB) { u32x4 w; w.x = cvt_pk_bf16(a.x, a.y); w.y = cvt_pk_bf16(a.z, a.w); w.z = cvt_pk_bf16(b.x, b.y); w.w = cvt_pk_bf16(b.z, b.w); *(u32x4*)(dstB + (size_t)r * 1024 + c) = w; }
;         if (ss) { float s2 = (a.x * a.x + a.y * a.y) + (a.z * a.z + a.w * a.w) + (b.x * b.x + b.y * b.y) + (b.z * b.z + b.w * b.w);
;             s2 += __shfl_xor(s2, 1); s2 += __shfl_xor(s2, 2); s2 += __shfl_xor(s2, 4); if ((c & 63) == 0) atomicAdd(ss + r, s2); }
; template <int K, class Epi> __device__ __forceinline__ void gemm_small2_rc(const bf16_t* A, const bf16_t* Bt, int row0, int col0, int wave, int lane, const Epi& E, unsigned char* lds) {
;     ...
;     __syncthreads();
;     {
;         const int t = wave * 64 + lane, r = t >> 3, c8 = t & 7;
;         f32x4 v0 = {0.f, 0.f, 0.f, 0.f}, v1 = {0.f, 0.f, 0.f, 0.f};
; #pragma unroll
;         for (int w = 0; w < 8; ++w) { const float* sp = (const float*)lds + w * 4096 + r * 64;
;             v0 += *(const f32x4*)(sp + 4 * ((2 * c8) ^ (r & 15))); v1 += *(const f32x4*)(sp + 4 * ((2 * c8 + 1) ^ (r & 15))); }
;         E.small8(row0 + r, col0 + 8 * c8, v0, v1);
;     }
;     __syncthreads();
	global_load_dwordx4 v[0:3], v[44:45], off
	v_ashrrev_i32_e32 v63, 31, v62
	v_add_u32_e32 v6, 0x1c000, v98
	v_lshlrev_b32_e32 v7, 4, v76
	v_lshlrev_b64 v[4:5], 12, v[62:63]
	v_add_u32_e32 v24, v98, v100
	v_add_u32_e32 v36, v77, v100
	v_add_u32_e32 v44, v78, v100
	v_add_u32_e32 v64, v6, v100
	v_add_u32_e32 v32, v98, v7
	v_add_u32_e32 v40, v77, v7
	v_add_u32_e32 v48, v78, v7
	v_add_u32_e32 v60, v50, v7
	v_add_u32_e32 v68, v6, v7
	v_lshl_add_u64 v[4:5], s[8:9], 0, v[4:5]
	v_lshl_add_u64 v[72:73], v[4:5], 0, v[52:53]
	ds_read_b128 v[4:7], v24
	ds_read_b128 v[8:11], v24 offset:16384
	ds_read_b128 v[12:15], v32
	ds_read_b128 v[16:19], v32 offset:16384
	ds_read_b128 v[20:23], v24 offset:32768
	ds_read_b128 v[24:27], v24 offset:49152
	ds_read_b128 v[28:31], v32 offset:32768
	ds_read_b128 v[32:35], v32 offset:49152
	ds_read_b128 v[36:39], v36
	ds_read_b128 v[40:43], v40
	ds_read_b128 v[44:47], v44
	ds_read_b128 v[48:51], v48
	ds_read_b128 v[56:59], v56
	ds_read_b128 v[60:63], v60
	ds_read_b128 v[64:67], v64
	ds_read_b128 v[68:71], v68
	s_waitcnt lgkmcnt(14)
	v_pk_add_f32 v[6:7], v[6:7], 0 op_sel_hi:[1,0]
	v_pk_add_f32 v[4:5], v[4:5], 0 op_sel_hi:[1,0]
	s_waitcnt lgkmcnt(13)
	v_pk_add_f32 v[14:15], v[14:15], 0 op_sel_hi:[1,0]
	v_pk_add_f32 v[12:13], v[12:13], 0 op_sel_hi:[1,0]
	v_pk_add_f32 v[6:7], v[6:7], v[10:11]
	v_pk_add_f32 v[4:5], v[4:5], v[8:9]
	s_waitcnt lgkmcnt(12)
	v_pk_add_f32 v[8:9], v[14:15], v[18:19]
	v_pk_add_f32 v[10:11], v[12:13], v[16:17]
	s_waitcnt lgkmcnt(11)
	v_pk_add_f32 v[6:7], v[6:7], v[22:23]
	v_pk_add_f32 v[4:5], v[4:5], v[20:21]
	s_waitcnt lgkmcnt(9)
	v_pk_add_f32 v[8:9], v[8:9], v[30:31]
	v_pk_add_f32 v[10:11], v[10:11], v[28:29]
	v_pk_add_f32 v[6:7], v[6:7], v[26:27]
	v_pk_add_f32 v[4:5], v[4:5], v[24:25]
	s_waitcnt lgkmcnt(8)
	v_pk_add_f32 v[8:9], v[8:9], v[34:35]
	v_pk_add_f32 v[10:11], v[10:11], v[32:33]
	s_waitcnt lgkmcnt(7)
	v_pk_add_f32 v[6:7], v[6:7], v[38:39]
	v_pk_add_f32 v[4:5], v[4:5], v[36:37]
	s_waitcnt lgkmcnt(6)
	v_pk_add_f32 v[8:9], v[8:9], v[42:43]
	v_pk_add_f32 v[10:11], v[10:11], v[40:41]
	s_waitcnt lgkmcnt(5)
	v_pk_add_f32 v[6:7], v[6:7], v[46:47]
	v_pk_add_f32 v[4:5], v[4:5], v[44:45]
	s_waitcnt lgkmcnt(4)
	v_pk_add_f32 v[8:9], v[8:9], v[50:51]
	v_pk_add_f32 v[10:11], v[10:11], v[48:49]
	s_waitcnt lgkmcnt(3)
	v_pk_add_f32 v[6:7], v[6:7], v[58:59]
	v_pk_add_f32 v[4:5], v[4:5], v[56:57]
	s_waitcnt lgkmcnt(2)
	v_pk_add_f32 v[8:9], v[8:9], v[62:63]
	v_pk_add_f32 v[10:11], v[10:11], v[60:61]
	s_waitcnt lgkmcnt(1)
	v_pk_add_f32 v[6:7], v[6:7], v[66:67]
	v_pk_add_f32 v[4:5], v[4:5], v[64:65]
	s_waitcnt lgkmcnt(0)
	v_pk_add_f32 v[8:9], v[8:9], v[70:71]
	v_pk_add_f32 v[10:11], v[10:11], v[68:69]
	s_waitcnt vmcnt(0)
	v_lshlrev_b32_e32 v12, 16, v0
	v_and_b32_e32 v13, 0xffff0000, v0
	v_lshlrev_b32_e32 v0, 16, v1
	v_and_b32_e32 v1, 0xffff0000, v1
	v_lshlrev_b32_e32 v14, 16, v2
	v_and_b32_e32 v15, 0xffff0000, v2
	v_lshlrev_b32_e32 v16, 16, v3
	v_and_b32_e32 v17, 0xffff0000, v3
	v_pk_add_f32 v[2:3], v[6:7], v[0:1]
	v_pk_add_f32 v[0:1], v[4:5], v[12:13]
	v_pk_add_f32 v[6:7], v[8:9], v[16:17]
	v_pk_add_f32 v[4:5], v[10:11], v[14:15]
	global_store_dwordx4 v[72:73], v[0:3], off
	global_store_dwordx4 v[72:73], v[4:7], off offset:16
	s_barrier
	s_cbranch_scc1 .LBB0_3625
